# fix-up phase: the two 16-byte loads of a lane's packed h_loc/p_cum row segment no longer carry the nt hint (the second one now hits the line the first brought in)
# baseline (speedup 1.0000x reference)
; __device__ __forceinline__ u32x4 pack8(const float (&f)[8]) { u32x4 o; o.x = cvt_pk_bf16(f[0], f[1]); o.y = cvt_pk_bf16(f[2], f[3]); o.z = cvt_pk_bf16(f[4], f[5]); o.w = cvt_pk_bf16(f[6], f[7]); return o; }
; __device__ __forceinline__ float gelu_tanh(float x) { return x * sigmoidf_(1.5957691216057308f * (x + 0.044715f * x * x * x)); }
; __device__ __forceinline__ void fixup_phase(KP p, int l) {
;     ...
; #pragma unroll 4
;         for (int i = 0; i < 16; ++i) {
;             const size_t m = (size_t)(m0 + i);
;             float hl[8], pc[8], gr[8], o[8], h[8];
;             unpack8(__builtin_nontemporal_load((const u32x4*)(HLOC + m * D + c0)), hl); unpack8(__builtin_nontemporal_load((const u32x4*)(PCUM + m * D + c0)), pc);
;             bf16_t* gp = P + m * DP + C_GR + c0; unpack8(*(const u32x4*)gp, gr);
; #pragma unroll
;             for (int e = 0; e < 8; ++e) { h[e] = hl[e] + pc[e] * carry[e]; o[e] = gelu_tanh(gr[e]) * h[e]; }
;             *(u32x4*)gp = pack8(o);
;             if (tile < 1032 && t0 + i == TP - 1) store8f(p->out + O_PRG + (size_t)(l * NB + b) * D + c0, h);
.Lfx_nocarry:
	s_lshl_b32 s44, s48, 12
	s_add_u32 s12, s34, 0x14a48000
	s_addc_u32 s13, s35, 0
	s_add_u32 s12, s12, s44
	s_addc_u32 s13, s13, 0
	s_add_u32 s14, s12, 0x2080000
	s_addc_u32 s15, s13, 0
	s_mul_i32 s44, s48, 0x2800
	s_add_u32 s96, s34, 0x66c9800
	s_addc_u32 s97, s35, 0
	s_add_u32 s96, s96, s44
	s_addc_u32 s97, s97, 0
	s_mov_b32 s24, s96
	s_mov_b32 s25, s97
	global_load_dwordx4 v[32:35], v31, s[12:13]
	global_load_dwordx4 v[36:39], v31, s[12:13] offset:16
	global_load_dwordx4 v[40:43], v26, s[96:97] nt
	s_add_u32 s12, s12, 0x1000
	s_addc_u32 s13, s13, 0
	s_add_u32 s96, s96, 0x2800
	s_addc_u32 s97, s97, 0
	global_load_dwordx4 v[44:47], v31, s[12:13]
	global_load_dwordx4 v[48:51], v31, s[12:13] offset:16
	global_load_dwordx4 v[52:55], v26, s[96:97] nt
	s_add_u32 s12, s12, 0x1000
	s_addc_u32 s13, s13, 0
	s_add_u32 s96, s96, 0x2800
	s_addc_u32 s97, s97, 0
	global_load_dwordx4 v[56:59], v31, s[12:13]
	global_load_dwordx4 v[60:63], v31, s[12:13] offset:16
	global_load_dwordx4 v[64:67], v26, s[96:97] nt
	s_add_u32 s12, s12, 0x1000
	s_addc_u32 s13, s13, 0
	s_add_u32 s96, s96, 0x2800
	s_addc_u32 s97, s97, 0
	global_load_dwordx4 v[68:71], v31, s[12:13]
	global_load_dwordx4 v[72:75], v31, s[12:13] offset:16
	global_load_dwordx4 v[76:79], v26, s[96:97] nt
	s_add_u32 s12, s12, 0x1000
	s_addc_u32 s13, s13, 0
	s_add_u32 s96, s96, 0x2800
	s_addc_u32 s97, s97, 0
	s_waitcnt vmcnt(9)
	v_lshlrev_b32_e32 v80, 16, v32
	v_and_b32_e32 v96, 0xffff0000, v32
	v_lshlrev_b32_e32 v81, 16, v33
	v_and_b32_e32 v97, 0xffff0000, v33
	v_lshlrev_b32_e32 v82, 16, v34
	v_and_b32_e32 v98, 0xffff0000, v34
	v_lshlrev_b32_e32 v83, 16, v35
	v_and_b32_e32 v99, 0xffff0000, v35
	v_lshlrev_b32_e32 v84, 16, v36
	v_and_b32_e32 v100, 0xffff0000, v36
	v_lshlrev_b32_e32 v85, 16, v37
	v_and_b32_e32 v101, 0xffff0000, v37
	v_lshlrev_b32_e32 v86, 16, v38
	v_and_b32_e32 v102, 0xffff0000, v38
	v_lshlrev_b32_e32 v87, 16, v39
	v_and_b32_e32 v103, 0xffff0000, v39
	v_lshlrev_b32_e32 v88, 16, v40
	v_and_b32_e32 v89, 0xffff0000, v40
	v_lshlrev_b32_e32 v90, 16, v41
	v_and_b32_e32 v91, 0xffff0000, v41
	v_lshlrev_b32_e32 v92, 16, v42
	v_and_b32_e32 v93, 0xffff0000, v42
	v_lshlrev_b32_e32 v94, 16, v43
	v_and_b32_e32 v95, 0xffff0000, v43
	v_fmac_f32_e32 v80, v96, v18
	v_fmac_f32_e32 v81, v97, v19
	v_fmac_f32_e32 v82, v98, v20
	v_fmac_f32_e32 v83, v99, v21
	v_fmac_f32_e32 v84, v100, v22
	v_fmac_f32_e32 v85, v101, v23
	v_fmac_f32_e32 v86, v102, v24
	v_fmac_f32_e32 v87, v103, v25
	v_mul_f32_e32 v104, 0x3d372713, v88
	v_mul_f32_e32 v105, 0x3d372713, v89
	v_mul_f32_e32 v106, 0x3d372713, v90
	v_mul_f32_e32 v107, 0x3d372713, v91
	v_mul_f32_e32 v108, 0x3d372713, v92
	v_mul_f32_e32 v109, 0x3d372713, v93
	v_mul_f32_e32 v110, 0x3d372713, v94
	v_mul_f32_e32 v111, 0x3d372713, v95
	v_mul_f32_e32 v104, v104, v88
	v_mul_f32_e32 v105, v105, v89
	v_mul_f32_e32 v106, v106, v90
	v_mul_f32_e32 v107, v107, v91
	v_mul_f32_e32 v108, v108, v92
	v_mul_f32_e32 v109, v109, v93
	v_mul_f32_e32 v110, v110, v94
	v_mul_f32_e32 v111, v111, v95
	v_fma_f32 v104, v104, v88, v88
	v_fma_f32 v105, v105, v89, v89
	v_fma_f32 v106, v106, v90, v90
	v_fma_f32 v107, v107, v91, v91
	v_fma_f32 v108, v108, v92, v92
	v_fma_f32 v109, v109, v93, v93
	v_fma_f32 v110, v110, v94, v94
	v_fma_f32 v111, v111, v95, v95
	v_mul_f32_e32 v104, 0x3fcc422a, v104
	v_mul_f32_e32 v105, 0x3fcc422a, v105
	v_mul_f32_e32 v106, 0x3fcc422a, v106
	v_mul_f32_e32 v107, 0x3fcc422a, v107
	v_mul_f32_e32 v108, 0x3fcc422a, v108
	v_mul_f32_e32 v109, 0x3fcc422a, v109
	v_mul_f32_e32 v110, 0x3fcc422a, v110
	v_mul_f32_e32 v111, 0x3fcc422a, v111
	v_mul_f32_e32 v104, 0xbfb8aa3b, v104
	v_mul_f32_e32 v105, 0xbfb8aa3b, v105
	v_mul_f32_e32 v106, 0xbfb8aa3b, v106
	v_mul_f32_e32 v107, 0xbfb8aa3b, v107
	v_mul_f32_e32 v108, 0xbfb8aa3b, v108
	v_mul_f32_e32 v109, 0xbfb8aa3b, v109
	v_mul_f32_e32 v110, 0xbfb8aa3b, v110
	v_mul_f32_e32 v111, 0xbfb8aa3b, v111
	v_exp_f32_e32 v104, v104
	v_exp_f32_e32 v105, v105
	v_exp_f32_e32 v106, v106
	v_exp_f32_e32 v107, v107
	v_exp_f32_e32 v108, v108
	v_exp_f32_e32 v109, v109
	v_exp_f32_e32 v110, v110
	v_exp_f32_e32 v111, v111
	v_add_f32_e32 v104, 1.0, v104
	v_add_f32_e32 v105, 1.0, v105
	v_add_f32_e32 v106, 1.0, v106
	v_add_f32_e32 v107, 1.0, v107
	v_add_f32_e32 v108, 1.0, v108
	v_add_f32_e32 v109, 1.0, v109
	v_add_f32_e32 v110, 1.0, v110
	v_add_f32_e32 v111, 1.0, v111
	v_rcp_f32_e32 v104, v104
	v_rcp_f32_e32 v105, v105
	v_rcp_f32_e32 v106, v106
	v_rcp_f32_e32 v107, v107
	v_rcp_f32_e32 v108, v108
	v_rcp_f32_e32 v109, v109
	v_rcp_f32_e32 v110, v110
	v_rcp_f32_e32 v111, v111
	v_mul_f32_e32 v104, v104, v88
	v_mul_f32_e32 v105, v105, v89
	v_mul_f32_e32 v106, v106, v90
	v_mul_f32_e32 v107, v107, v91
	v_mul_f32_e32 v108, v108, v92
	v_mul_f32_e32 v109, v109, v93
	v_mul_f32_e32 v110, v110, v94
	v_mul_f32_e32 v111, v111, v95
	v_mul_f32_e32 v104, v80, v104
	v_mul_f32_e32 v105, v81, v105
	v_mul_f32_e32 v106, v82, v106
	v_mul_f32_e32 v107, v83, v107
	v_mul_f32_e32 v108, v84, v108
	v_mul_f32_e32 v109, v85, v109
	v_mul_f32_e32 v110, v86, v110
	v_mul_f32_e32 v111, v87, v111
	v_cvt_pk_bf16_f32 v112, v104, v105
	v_cvt_pk_bf16_f32 v113, v106, v107
	v_cvt_pk_bf16_f32 v114, v108, v109
	v_cvt_pk_bf16_f32 v115, v110, v111
	global_store_dwordx4 v27, v[112:115], s[24:25]
	s_add_u32 s24, s24, 0x2800
	s_addc_u32 s25, s25, 0
	global_load_dwordx4 v[32:35], v31, s[12:13]
	global_load_dwordx4 v[36:39], v31, s[12:13] offset:16
	global_load_dwordx4 v[40:43], v26, s[96:97] nt
	s_add_u32 s12, s12, 0x1000
	s_addc_u32 s13, s13, 0
	s_add_u32 s96, s96, 0x2800
	s_addc_u32 s97, s97, 0
	s_waitcnt vmcnt(10)
; __device__ __forceinline__ u32x4 pack8(const float (&f)[8]) { u32x4 o; o.x = cvt_pk_bf16(f[0], f[1]); o.y = cvt_pk_bf16(f[2], f[3]); o.z = cvt_pk_bf16(f[4], f[5]); o.w = cvt_pk_bf16(f[6], f[7]); return o; }
; __device__ __forceinline__ float gelu_tanh(float x) { return x * sigmoidf_(1.5957691216057308f * (x + 0.044715f * x * x * x)); }
; __device__ __forceinline__ void fixup_phase(KP p, int l) {
;     ...
; #pragma unroll 4
;         for (int i = 0; i < 16; ++i) {
;             const size_t m = (size_t)(m0 + i);
;             float hl[8], pc[8], gr[8], o[8], h[8];
;             unpack8(__builtin_nontemporal_load((const u32x4*)(HLOC + m * D + c0)), hl); unpack8(__builtin_nontemporal_load((const u32x4*)(PCUM + m * D + c0)), pc);
;             bf16_t* gp = P + m * DP + C_GR + c0; unpack8(*(const u32x4*)gp, gr);
; #pragma unroll
;             for (int e = 0; e < 8; ++e) { h[e] = hl[e] + pc[e] * carry[e]; o[e] = gelu_tanh(gr[e]) * h[e]; }
;             *(u32x4*)gp = pack8(o);
	v_lshlrev_b32_e32 v80, 16, v44
	v_and_b32_e32 v96, 0xffff0000, v44
	v_lshlrev_b32_e32 v81, 16, v45
	v_and_b32_e32 v97, 0xffff0000, v45
	v_lshlrev_b32_e32 v82, 16, v46
	v_and_b32_e32 v98, 0xffff0000, v46
	v_lshlrev_b32_e32 v83, 16, v47
	v_and_b32_e32 v99, 0xffff0000, v47
	v_lshlrev_b32_e32 v84, 16, v48
	v_and_b32_e32 v100, 0xffff0000, v48
	v_lshlrev_b32_e32 v85, 16, v49
	v_and_b32_e32 v101, 0xffff0000, v49
	v_lshlrev_b32_e32 v86, 16, v50
	v_and_b32_e32 v102, 0xffff0000, v50
	v_lshlrev_b32_e32 v87, 16, v51
	v_and_b32_e32 v103, 0xffff0000, v51
	v_lshlrev_b32_e32 v88, 16, v52
	v_and_b32_e32 v89, 0xffff0000, v52
	v_lshlrev_b32_e32 v90, 16, v53
	v_and_b32_e32 v91, 0xffff0000, v53
	v_lshlrev_b32_e32 v92, 16, v54
	v_and_b32_e32 v93, 0xffff0000, v54
	v_lshlrev_b32_e32 v94, 16, v55
	v_and_b32_e32 v95, 0xffff0000, v55
	v_fmac_f32_e32 v80, v96, v18
	v_fmac_f32_e32 v81, v97, v19
	v_fmac_f32_e32 v82, v98, v20
	v_fmac_f32_e32 v83, v99, v21
	v_fmac_f32_e32 v84, v100, v22
	v_fmac_f32_e32 v85, v101, v23
	v_fmac_f32_e32 v86, v102, v24
	v_fmac_f32_e32 v87, v103, v25
	v_mul_f32_e32 v104, 0x3d372713, v88
	v_mul_f32_e32 v105, 0x3d372713, v89
	v_mul_f32_e32 v106, 0x3d372713, v90
	v_mul_f32_e32 v107, 0x3d372713, v91
	v_mul_f32_e32 v108, 0x3d372713, v92
	v_mul_f32_e32 v109, 0x3d372713, v93
	v_mul_f32_e32 v110, 0x3d372713, v94
	v_mul_f32_e32 v111, 0x3d372713, v95
	v_mul_f32_e32 v104, v104, v88
	v_mul_f32_e32 v105, v105, v89
	v_mul_f32_e32 v106, v106, v90
	v_mul_f32_e32 v107, v107, v91
	v_mul_f32_e32 v108, v108, v92
	v_mul_f32_e32 v109, v109, v93
	v_mul_f32_e32 v110, v110, v94
	v_mul_f32_e32 v111, v111, v95
	v_fma_f32 v104, v104, v88, v88
	v_fma_f32 v105, v105, v89, v89
	v_fma_f32 v106, v106, v90, v90
	v_fma_f32 v107, v107, v91, v91
	v_fma_f32 v108, v108, v92, v92
	v_fma_f32 v109, v109, v93, v93
	v_fma_f32 v110, v110, v94, v94
	v_fma_f32 v111, v111, v95, v95
	v_mul_f32_e32 v104, 0x3fcc422a, v104
	v_mul_f32_e32 v105, 0x3fcc422a, v105
	v_mul_f32_e32 v106, 0x3fcc422a, v106
	v_mul_f32_e32 v107, 0x3fcc422a, v107
	v_mul_f32_e32 v108, 0x3fcc422a, v108
	v_mul_f32_e32 v109, 0x3fcc422a, v109
	v_mul_f32_e32 v110, 0x3fcc422a, v110
	v_mul_f32_e32 v111, 0x3fcc422a, v111
	v_mul_f32_e32 v104, 0xbfb8aa3b, v104
	v_mul_f32_e32 v105, 0xbfb8aa3b, v105
	v_mul_f32_e32 v106, 0xbfb8aa3b, v106
	v_mul_f32_e32 v107, 0xbfb8aa3b, v107
	v_mul_f32_e32 v108, 0xbfb8aa3b, v108
	v_mul_f32_e32 v109, 0xbfb8aa3b, v109
	v_mul_f32_e32 v110, 0xbfb8aa3b, v110
	v_mul_f32_e32 v111, 0xbfb8aa3b, v111
	v_exp_f32_e32 v104, v104
	v_exp_f32_e32 v105, v105
	v_exp_f32_e32 v106, v106
	v_exp_f32_e32 v107, v107
	v_exp_f32_e32 v108, v108
	v_exp_f32_e32 v109, v109
	v_exp_f32_e32 v110, v110
	v_exp_f32_e32 v111, v111
	v_add_f32_e32 v104, 1.0, v104
	v_add_f32_e32 v105, 1.0, v105
	v_add_f32_e32 v106, 1.0, v106
	v_add_f32_e32 v107, 1.0, v107
	v_add_f32_e32 v108, 1.0, v108
	v_add_f32_e32 v109, 1.0, v109
	v_add_f32_e32 v110, 1.0, v110
	v_add_f32_e32 v111, 1.0, v111
	v_rcp_f32_e32 v104, v104
	v_rcp_f32_e32 v105, v105
	v_rcp_f32_e32 v106, v106
	v_rcp_f32_e32 v107, v107
	v_rcp_f32_e32 v108, v108
	v_rcp_f32_e32 v109, v109
	v_rcp_f32_e32 v110, v110
	v_rcp_f32_e32 v111, v111
	v_mul_f32_e32 v104, v104, v88
	v_mul_f32_e32 v105, v105, v89
	v_mul_f32_e32 v106, v106, v90
	v_mul_f32_e32 v107, v107, v91
	v_mul_f32_e32 v108, v108, v92
	v_mul_f32_e32 v109, v109, v93
	v_mul_f32_e32 v110, v110, v94
	v_mul_f32_e32 v111, v111, v95
	v_mul_f32_e32 v104, v80, v104
	v_mul_f32_e32 v105, v81, v105
	v_mul_f32_e32 v106, v82, v106
	v_mul_f32_e32 v107, v83, v107
	v_mul_f32_e32 v108, v84, v108
	v_mul_f32_e32 v109, v85, v109
	v_mul_f32_e32 v110, v86, v110
	v_mul_f32_e32 v111, v87, v111
	v_cvt_pk_bf16_f32 v112, v104, v105
	v_cvt_pk_bf16_f32 v113, v106, v107
	v_cvt_pk_bf16_f32 v114, v108, v109
	v_cvt_pk_bf16_f32 v115, v110, v111
	global_store_dwordx4 v27, v[112:115], s[24:25]
	s_add_u32 s24, s24, 0x2800
	s_addc_u32 s25, s25, 0
	global_load_dwordx4 v[44:47], v31, s[12:13]
	global_load_dwordx4 v[48:51], v31, s[12:13] offset:16
	global_load_dwordx4 v[52:55], v26, s[96:97] nt
	s_add_u32 s12, s12, 0x1000
	s_addc_u32 s13, s13, 0
	s_add_u32 s96, s96, 0x2800
	s_addc_u32 s97, s97, 0
	s_waitcnt vmcnt(11)
	v_lshlrev_b32_e32 v80, 16, v56
	v_and_b32_e32 v96, 0xffff0000, v56
	v_lshlrev_b32_e32 v81, 16, v57
	v_and_b32_e32 v97, 0xffff0000, v57
	v_lshlrev_b32_e32 v82, 16, v58
	v_and_b32_e32 v98, 0xffff0000, v58
	v_lshlrev_b32_e32 v83, 16, v59
	v_and_b32_e32 v99, 0xffff0000, v59
	v_lshlrev_b32_e32 v84, 16, v60
	v_and_b32_e32 v100, 0xffff0000, v60
	v_lshlrev_b32_e32 v85, 16, v61
	v_and_b32_e32 v101, 0xffff0000, v61
	v_lshlrev_b32_e32 v86, 16, v62
	v_and_b32_e32 v102, 0xffff0000, v62
	v_lshlrev_b32_e32 v87, 16, v63
	v_and_b32_e32 v103, 0xffff0000, v63
	v_lshlrev_b32_e32 v88, 16, v64
	v_and_b32_e32 v89, 0xffff0000, v64
	v_lshlrev_b32_e32 v90, 16, v65
	v_and_b32_e32 v91, 0xffff0000, v65
	v_lshlrev_b32_e32 v92, 16, v66
	v_and_b32_e32 v93, 0xffff0000, v66
	v_lshlrev_b32_e32 v94, 16, v67
	v_and_b32_e32 v95, 0xffff0000, v67
	v_fmac_f32_e32 v80, v96, v18
	v_fmac_f32_e32 v81, v97, v19
	v_fmac_f32_e32 v82, v98, v20
	v_fmac_f32_e32 v83, v99, v21
	v_fmac_f32_e32 v84, v100, v22
	v_fmac_f32_e32 v85, v101, v23
	v_fmac_f32_e32 v86, v102, v24
	v_fmac_f32_e32 v87, v103, v25
	v_mul_f32_e32 v104, 0x3d372713, v88
	v_mul_f32_e32 v105, 0x3d372713, v89
	v_mul_f32_e32 v106, 0x3d372713, v90
	v_mul_f32_e32 v107, 0x3d372713, v91
	v_mul_f32_e32 v108, 0x3d372713, v92
	v_mul_f32_e32 v109, 0x3d372713, v93
	v_mul_f32_e32 v110, 0x3d372713, v94
	v_mul_f32_e32 v111, 0x3d372713, v95
	v_mul_f32_e32 v104, v104, v88
	v_mul_f32_e32 v105, v105, v89
	v_mul_f32_e32 v106, v106, v90
	v_mul_f32_e32 v107, v107, v91
; __device__ __forceinline__ u32x4 pack8(const float (&f)[8]) { u32x4 o; o.x = cvt_pk_bf16(f[0], f[1]); o.y = cvt_pk_bf16(f[2], f[3]); o.z = cvt_pk_bf16(f[4], f[5]); o.w = cvt_pk_bf16(f[6], f[7]); return o; }
; __device__ __forceinline__ float gelu_tanh(float x) { return x * sigmoidf_(1.5957691216057308f * (x + 0.044715f * x * x * x)); }
; __device__ __forceinline__ void fixup_phase(KP p, int l) {
;     ...
;         for (int i = 0; i < 16; ++i) {
;             const size_t m = (size_t)(m0 + i);
;             float hl[8], pc[8], gr[8], o[8], h[8];
;             unpack8(__builtin_nontemporal_load((const u32x4*)(HLOC + m * D + c0)), hl); unpack8(__builtin_nontemporal_load((const u32x4*)(PCUM + m * D + c0)), pc);
;             bf16_t* gp = P + m * DP + C_GR + c0; unpack8(*(const u32x4*)gp, gr);
; #pragma unroll
;             for (int e = 0; e < 8; ++e) { h[e] = hl[e] + pc[e] * carry[e]; o[e] = gelu_tanh(gr[e]) * h[e]; }
;             *(u32x4*)gp = pack8(o);
	v_mul_f32_e32 v108, v108, v92
	v_mul_f32_e32 v109, v109, v93
	v_mul_f32_e32 v110, v110, v94
	v_mul_f32_e32 v111, v111, v95
	v_fma_f32 v104, v104, v88, v88
	v_fma_f32 v105, v105, v89, v89
	v_fma_f32 v106, v106, v90, v90
	v_fma_f32 v107, v107, v91, v91
	v_fma_f32 v108, v108, v92, v92
	v_fma_f32 v109, v109, v93, v93
	v_fma_f32 v110, v110, v94, v94
	v_fma_f32 v111, v111, v95, v95
	v_mul_f32_e32 v104, 0x3fcc422a, v104
	v_mul_f32_e32 v105, 0x3fcc422a, v105
	v_mul_f32_e32 v106, 0x3fcc422a, v106
	v_mul_f32_e32 v107, 0x3fcc422a, v107
	v_mul_f32_e32 v108, 0x3fcc422a, v108
	v_mul_f32_e32 v109, 0x3fcc422a, v109
	v_mul_f32_e32 v110, 0x3fcc422a, v110
	v_mul_f32_e32 v111, 0x3fcc422a, v111
	v_mul_f32_e32 v104, 0xbfb8aa3b, v104
	v_mul_f32_e32 v105, 0xbfb8aa3b, v105
	v_mul_f32_e32 v106, 0xbfb8aa3b, v106
	v_mul_f32_e32 v107, 0xbfb8aa3b, v107
	v_mul_f32_e32 v108, 0xbfb8aa3b, v108
	v_mul_f32_e32 v109, 0xbfb8aa3b, v109
	v_mul_f32_e32 v110, 0xbfb8aa3b, v110
	v_mul_f32_e32 v111, 0xbfb8aa3b, v111
	v_exp_f32_e32 v104, v104
	v_exp_f32_e32 v105, v105
	v_exp_f32_e32 v106, v106
	v_exp_f32_e32 v107, v107
	v_exp_f32_e32 v108, v108
	v_exp_f32_e32 v109, v109
	v_exp_f32_e32 v110, v110
	v_exp_f32_e32 v111, v111
	v_add_f32_e32 v104, 1.0, v104
	v_add_f32_e32 v105, 1.0, v105
	v_add_f32_e32 v106, 1.0, v106
	v_add_f32_e32 v107, 1.0, v107
	v_add_f32_e32 v108, 1.0, v108
	v_add_f32_e32 v109, 1.0, v109
	v_add_f32_e32 v110, 1.0, v110
	v_add_f32_e32 v111, 1.0, v111
	v_rcp_f32_e32 v104, v104
	v_rcp_f32_e32 v105, v105
	v_rcp_f32_e32 v106, v106
	v_rcp_f32_e32 v107, v107
	v_rcp_f32_e32 v108, v108
	v_rcp_f32_e32 v109, v109
	v_rcp_f32_e32 v110, v110
	v_rcp_f32_e32 v111, v111
	v_mul_f32_e32 v104, v104, v88
	v_mul_f32_e32 v105, v105, v89
	v_mul_f32_e32 v106, v106, v90
	v_mul_f32_e32 v107, v107, v91
	v_mul_f32_e32 v108, v108, v92
	v_mul_f32_e32 v109, v109, v93
	v_mul_f32_e32 v110, v110, v94
	v_mul_f32_e32 v111, v111, v95
	v_mul_f32_e32 v104, v80, v104
	v_mul_f32_e32 v105, v81, v105
	v_mul_f32_e32 v106, v82, v106
	v_mul_f32_e32 v107, v83, v107
	v_mul_f32_e32 v108, v84, v108
	v_mul_f32_e32 v109, v85, v109
	v_mul_f32_e32 v110, v86, v110
	v_mul_f32_e32 v111, v87, v111
	v_cvt_pk_bf16_f32 v112, v104, v105
	v_cvt_pk_bf16_f32 v113, v106, v107
	v_cvt_pk_bf16_f32 v114, v108, v109
	v_cvt_pk_bf16_f32 v115, v110, v111
	global_store_dwordx4 v27, v[112:115], s[24:25]
	s_add_u32 s24, s24, 0x2800
	s_addc_u32 s25, s25, 0
	global_load_dwordx4 v[56:59], v31, s[12:13]
	global_load_dwordx4 v[60:63], v31, s[12:13] offset:16
	global_load_dwordx4 v[64:67], v26, s[96:97] nt
	s_add_u32 s12, s12, 0x1000
	s_addc_u32 s13, s13, 0
	s_add_u32 s96, s96, 0x2800
	s_addc_u32 s97, s97, 0
	s_waitcnt vmcnt(12)
	v_lshlrev_b32_e32 v80, 16, v68
	v_and_b32_e32 v96, 0xffff0000, v68
	v_lshlrev_b32_e32 v81, 16, v69
	v_and_b32_e32 v97, 0xffff0000, v69
	v_lshlrev_b32_e32 v82, 16, v70
	v_and_b32_e32 v98, 0xffff0000, v70
	v_lshlrev_b32_e32 v83, 16, v71
	v_and_b32_e32 v99, 0xffff0000, v71
	v_lshlrev_b32_e32 v84, 16, v72
	v_and_b32_e32 v100, 0xffff0000, v72
	v_lshlrev_b32_e32 v85, 16, v73
	v_and_b32_e32 v101, 0xffff0000, v73
	v_lshlrev_b32_e32 v86, 16, v74
	v_and_b32_e32 v102, 0xffff0000, v74
	v_lshlrev_b32_e32 v87, 16, v75
	v_and_b32_e32 v103, 0xffff0000, v75
	v_lshlrev_b32_e32 v88, 16, v76
	v_and_b32_e32 v89, 0xffff0000, v76
	v_lshlrev_b32_e32 v90, 16, v77
	v_and_b32_e32 v91, 0xffff0000, v77
	v_lshlrev_b32_e32 v92, 16, v78
	v_and_b32_e32 v93, 0xffff0000, v78
	v_lshlrev_b32_e32 v94, 16, v79
	v_and_b32_e32 v95, 0xffff0000, v79
	v_fmac_f32_e32 v80, v96, v18
	v_fmac_f32_e32 v81, v97, v19
	v_fmac_f32_e32 v82, v98, v20
	v_fmac_f32_e32 v83, v99, v21
	v_fmac_f32_e32 v84, v100, v22
	v_fmac_f32_e32 v85, v101, v23
	v_fmac_f32_e32 v86, v102, v24
	v_fmac_f32_e32 v87, v103, v25
	v_mul_f32_e32 v104, 0x3d372713, v88
	v_mul_f32_e32 v105, 0x3d372713, v89
	v_mul_f32_e32 v106, 0x3d372713, v90
	v_mul_f32_e32 v107, 0x3d372713, v91
	v_mul_f32_e32 v108, 0x3d372713, v92
	v_mul_f32_e32 v109, 0x3d372713, v93
	v_mul_f32_e32 v110, 0x3d372713, v94
	v_mul_f32_e32 v111, 0x3d372713, v95
	v_mul_f32_e32 v104, v104, v88
	v_mul_f32_e32 v105, v105, v89
	v_mul_f32_e32 v106, v106, v90
	v_mul_f32_e32 v107, v107, v91
	v_mul_f32_e32 v108, v108, v92
	v_mul_f32_e32 v109, v109, v93
	v_mul_f32_e32 v110, v110, v94
	v_mul_f32_e32 v111, v111, v95
	v_fma_f32 v104, v104, v88, v88
	v_fma_f32 v105, v105, v89, v89
	v_fma_f32 v106, v106, v90, v90
	v_fma_f32 v107, v107, v91, v91
	v_fma_f32 v108, v108, v92, v92
	v_fma_f32 v109, v109, v93, v93
	v_fma_f32 v110, v110, v94, v94
	v_fma_f32 v111, v111, v95, v95
	v_mul_f32_e32 v104, 0x3fcc422a, v104
	v_mul_f32_e32 v105, 0x3fcc422a, v105
	v_mul_f32_e32 v106, 0x3fcc422a, v106
	v_mul_f32_e32 v107, 0x3fcc422a, v107
	v_mul_f32_e32 v108, 0x3fcc422a, v108
	v_mul_f32_e32 v109, 0x3fcc422a, v109
	v_mul_f32_e32 v110, 0x3fcc422a, v110
	v_mul_f32_e32 v111, 0x3fcc422a, v111
	v_mul_f32_e32 v104, 0xbfb8aa3b, v104
	v_mul_f32_e32 v105, 0xbfb8aa3b, v105
	v_mul_f32_e32 v106, 0xbfb8aa3b, v106
	v_mul_f32_e32 v107, 0xbfb8aa3b, v107
	v_mul_f32_e32 v108, 0xbfb8aa3b, v108
	v_mul_f32_e32 v109, 0xbfb8aa3b, v109
	v_mul_f32_e32 v110, 0xbfb8aa3b, v110
	v_mul_f32_e32 v111, 0xbfb8aa3b, v111
	v_exp_f32_e32 v104, v104
	v_exp_f32_e32 v105, v105
	v_exp_f32_e32 v106, v106
	v_exp_f32_e32 v107, v107
	v_exp_f32_e32 v108, v108
	v_exp_f32_e32 v109, v109
	v_exp_f32_e32 v110, v110
	v_exp_f32_e32 v111, v111
	v_add_f32_e32 v104, 1.0, v104
	v_add_f32_e32 v105, 1.0, v105
	v_add_f32_e32 v106, 1.0, v106
	v_add_f32_e32 v107, 1.0, v107
	v_add_f32_e32 v108, 1.0, v108
	v_add_f32_e32 v109, 1.0, v109
	v_add_f32_e32 v110, 1.0, v110
	v_add_f32_e32 v111, 1.0, v111
	v_rcp_f32_e32 v104, v104
	v_rcp_f32_e32 v105, v105
	v_rcp_f32_e32 v106, v106
	v_rcp_f32_e32 v107, v107
	v_rcp_f32_e32 v108, v108
	v_rcp_f32_e32 v109, v109
	v_rcp_f32_e32 v110, v110
	v_rcp_f32_e32 v111, v111
	v_mul_f32_e32 v104, v104, v88
	v_mul_f32_e32 v105, v105, v89
	v_mul_f32_e32 v106, v106, v90
	v_mul_f32_e32 v107, v107, v91
	v_mul_f32_e32 v108, v108, v92
	v_mul_f32_e32 v109, v109, v93
	v_mul_f32_e32 v110, v110, v94
	v_mul_f32_e32 v111, v111, v95
	v_mul_f32_e32 v104, v80, v104
	v_mul_f32_e32 v105, v81, v105
	v_mul_f32_e32 v106, v82, v106
	v_mul_f32_e32 v107, v83, v107
	v_mul_f32_e32 v108, v84, v108
	v_mul_f32_e32 v109, v85, v109
	v_mul_f32_e32 v110, v86, v110
	v_mul_f32_e32 v111, v87, v111
	v_cvt_pk_bf16_f32 v112, v104, v105
	v_cvt_pk_bf16_f32 v113, v106, v107
	v_cvt_pk_bf16_f32 v114, v108, v109
	v_cvt_pk_bf16_f32 v115, v110, v111
	global_store_dwordx4 v27, v[112:115], s[24:25]
	s_add_u32 s24, s24, 0x2800
	s_addc_u32 s25, s25, 0
	global_load_dwordx4 v[68:71], v31, s[12:13]
	global_load_dwordx4 v[72:75], v31, s[12:13] offset:16
	global_load_dwordx4 v[76:79], v26, s[96:97] nt
	s_add_u32 s12, s12, 0x1000
	s_addc_u32 s13, s13, 0
	s_add_u32 s96, s96, 0x2800
	s_addc_u32 s97, s97, 0
	s_waitcnt vmcnt(12)
; __device__ __forceinline__ u32x4 pack8(const float (&f)[8]) { u32x4 o; o.x = cvt_pk_bf16(f[0], f[1]); o.y = cvt_pk_bf16(f[2], f[3]); o.z = cvt_pk_bf16(f[4], f[5]); o.w = cvt_pk_bf16(f[6], f[7]); return o; }
; __device__ __forceinline__ float gelu_tanh(float x) { return x * sigmoidf_(1.5957691216057308f * (x + 0.044715f * x * x * x)); }
; __device__ __forceinline__ void fixup_phase(KP p, int l) {
;     ...
;         for (int i = 0; i < 16; ++i) {
;             const size_t m = (size_t)(m0 + i);
;             float hl[8], pc[8], gr[8], o[8], h[8];
;             unpack8(__builtin_nontemporal_load((const u32x4*)(HLOC + m * D + c0)), hl); unpack8(__builtin_nontemporal_load((const u32x4*)(PCUM + m * D + c0)), pc);
;             bf16_t* gp = P + m * DP + C_GR + c0; unpack8(*(const u32x4*)gp, gr);
; #pragma unroll
;             for (int e = 0; e < 8; ++e) { h[e] = hl[e] + pc[e] * carry[e]; o[e] = gelu_tanh(gr[e]) * h[e]; }
;             *(u32x4*)gp = pack8(o);
	v_lshlrev_b32_e32 v80, 16, v32
	v_and_b32_e32 v96, 0xffff0000, v32
	v_lshlrev_b32_e32 v81, 16, v33
	v_and_b32_e32 v97, 0xffff0000, v33
	v_lshlrev_b32_e32 v82, 16, v34
	v_and_b32_e32 v98, 0xffff0000, v34
	v_lshlrev_b32_e32 v83, 16, v35
	v_and_b32_e32 v99, 0xffff0000, v35
	v_lshlrev_b32_e32 v84, 16, v36
	v_and_b32_e32 v100, 0xffff0000, v36
	v_lshlrev_b32_e32 v85, 16, v37
	v_and_b32_e32 v101, 0xffff0000, v37
	v_lshlrev_b32_e32 v86, 16, v38
	v_and_b32_e32 v102, 0xffff0000, v38
	v_lshlrev_b32_e32 v87, 16, v39
	v_and_b32_e32 v103, 0xffff0000, v39
	v_lshlrev_b32_e32 v88, 16, v40
	v_and_b32_e32 v89, 0xffff0000, v40
	v_lshlrev_b32_e32 v90, 16, v41
	v_and_b32_e32 v91, 0xffff0000, v41
	v_lshlrev_b32_e32 v92, 16, v42
	v_and_b32_e32 v93, 0xffff0000, v42
	v_lshlrev_b32_e32 v94, 16, v43
	v_and_b32_e32 v95, 0xffff0000, v43
	v_fmac_f32_e32 v80, v96, v18
	v_fmac_f32_e32 v81, v97, v19
	v_fmac_f32_e32 v82, v98, v20
	v_fmac_f32_e32 v83, v99, v21
	v_fmac_f32_e32 v84, v100, v22
	v_fmac_f32_e32 v85, v101, v23
	v_fmac_f32_e32 v86, v102, v24
	v_fmac_f32_e32 v87, v103, v25
	v_mul_f32_e32 v104, 0x3d372713, v88
	v_mul_f32_e32 v105, 0x3d372713, v89
	v_mul_f32_e32 v106, 0x3d372713, v90
	v_mul_f32_e32 v107, 0x3d372713, v91
	v_mul_f32_e32 v108, 0x3d372713, v92
	v_mul_f32_e32 v109, 0x3d372713, v93
	v_mul_f32_e32 v110, 0x3d372713, v94
	v_mul_f32_e32 v111, 0x3d372713, v95
	v_mul_f32_e32 v104, v104, v88
	v_mul_f32_e32 v105, v105, v89
	v_mul_f32_e32 v106, v106, v90
	v_mul_f32_e32 v107, v107, v91
	v_mul_f32_e32 v108, v108, v92
	v_mul_f32_e32 v109, v109, v93
	v_mul_f32_e32 v110, v110, v94
	v_mul_f32_e32 v111, v111, v95
	v_fma_f32 v104, v104, v88, v88
	v_fma_f32 v105, v105, v89, v89
	v_fma_f32 v106, v106, v90, v90
	v_fma_f32 v107, v107, v91, v91
	v_fma_f32 v108, v108, v92, v92
	v_fma_f32 v109, v109, v93, v93
	v_fma_f32 v110, v110, v94, v94
	v_fma_f32 v111, v111, v95, v95
	v_mul_f32_e32 v104, 0x3fcc422a, v104
	v_mul_f32_e32 v105, 0x3fcc422a, v105
	v_mul_f32_e32 v106, 0x3fcc422a, v106
	v_mul_f32_e32 v107, 0x3fcc422a, v107
	v_mul_f32_e32 v108, 0x3fcc422a, v108
	v_mul_f32_e32 v109, 0x3fcc422a, v109
	v_mul_f32_e32 v110, 0x3fcc422a, v110
	v_mul_f32_e32 v111, 0x3fcc422a, v111
	v_mul_f32_e32 v104, 0xbfb8aa3b, v104
	v_mul_f32_e32 v105, 0xbfb8aa3b, v105
	v_mul_f32_e32 v106, 0xbfb8aa3b, v106
	v_mul_f32_e32 v107, 0xbfb8aa3b, v107
	v_mul_f32_e32 v108, 0xbfb8aa3b, v108
	v_mul_f32_e32 v109, 0xbfb8aa3b, v109
	v_mul_f32_e32 v110, 0xbfb8aa3b, v110
	v_mul_f32_e32 v111, 0xbfb8aa3b, v111
	v_exp_f32_e32 v104, v104
	v_exp_f32_e32 v105, v105
	v_exp_f32_e32 v106, v106
	v_exp_f32_e32 v107, v107
	v_exp_f32_e32 v108, v108
	v_exp_f32_e32 v109, v109
	v_exp_f32_e32 v110, v110
	v_exp_f32_e32 v111, v111
	v_add_f32_e32 v104, 1.0, v104
	v_add_f32_e32 v105, 1.0, v105
	v_add_f32_e32 v106, 1.0, v106
	v_add_f32_e32 v107, 1.0, v107
	v_add_f32_e32 v108, 1.0, v108
	v_add_f32_e32 v109, 1.0, v109
	v_add_f32_e32 v110, 1.0, v110
	v_add_f32_e32 v111, 1.0, v111
	v_rcp_f32_e32 v104, v104
	v_rcp_f32_e32 v105, v105
	v_rcp_f32_e32 v106, v106
	v_rcp_f32_e32 v107, v107
	v_rcp_f32_e32 v108, v108
	v_rcp_f32_e32 v109, v109
	v_rcp_f32_e32 v110, v110
	v_rcp_f32_e32 v111, v111
	v_mul_f32_e32 v104, v104, v88
	v_mul_f32_e32 v105, v105, v89
	v_mul_f32_e32 v106, v106, v90
	v_mul_f32_e32 v107, v107, v91
	v_mul_f32_e32 v108, v108, v92
	v_mul_f32_e32 v109, v109, v93
	v_mul_f32_e32 v110, v110, v94
	v_mul_f32_e32 v111, v111, v95
	v_mul_f32_e32 v104, v80, v104
	v_mul_f32_e32 v105, v81, v105
	v_mul_f32_e32 v106, v82, v106
	v_mul_f32_e32 v107, v83, v107
	v_mul_f32_e32 v108, v84, v108
	v_mul_f32_e32 v109, v85, v109
	v_mul_f32_e32 v110, v86, v110
	v_mul_f32_e32 v111, v87, v111
	v_cvt_pk_bf16_f32 v112, v104, v105
	v_cvt_pk_bf16_f32 v113, v106, v107
	v_cvt_pk_bf16_f32 v114, v108, v109
	v_cvt_pk_bf16_f32 v115, v110, v111
	global_store_dwordx4 v27, v[112:115], s[24:25]
	s_add_u32 s24, s24, 0x2800
	s_addc_u32 s25, s25, 0
	global_load_dwordx4 v[32:35], v31, s[12:13]
	global_load_dwordx4 v[36:39], v31, s[12:13] offset:16
	global_load_dwordx4 v[40:43], v26, s[96:97] nt
	s_add_u32 s12, s12, 0x1000
	s_addc_u32 s13, s13, 0
	s_add_u32 s96, s96, 0x2800
	s_addc_u32 s97, s97, 0
	s_waitcnt vmcnt(12)
	v_lshlrev_b32_e32 v80, 16, v44
	v_and_b32_e32 v96, 0xffff0000, v44
	v_lshlrev_b32_e32 v81, 16, v45
	v_and_b32_e32 v97, 0xffff0000, v45
	v_lshlrev_b32_e32 v82, 16, v46
	v_and_b32_e32 v98, 0xffff0000, v46
	v_lshlrev_b32_e32 v83, 16, v47
	v_and_b32_e32 v99, 0xffff0000, v47
	v_lshlrev_b32_e32 v84, 16, v48
	v_and_b32_e32 v100, 0xffff0000, v48
	v_lshlrev_b32_e32 v85, 16, v49
	v_and_b32_e32 v101, 0xffff0000, v49
	v_lshlrev_b32_e32 v86, 16, v50
	v_and_b32_e32 v102, 0xffff0000, v50
	v_lshlrev_b32_e32 v87, 16, v51
	v_and_b32_e32 v103, 0xffff0000, v51
	v_lshlrev_b32_e32 v88, 16, v52
	v_and_b32_e32 v89, 0xffff0000, v52
	v_lshlrev_b32_e32 v90, 16, v53
	v_and_b32_e32 v91, 0xffff0000, v53
	v_lshlrev_b32_e32 v92, 16, v54
	v_and_b32_e32 v93, 0xffff0000, v54
	v_lshlrev_b32_e32 v94, 16, v55
	v_and_b32_e32 v95, 0xffff0000, v55
	v_fmac_f32_e32 v80, v96, v18
	v_fmac_f32_e32 v81, v97, v19
	v_fmac_f32_e32 v82, v98, v20
	v_fmac_f32_e32 v83, v99, v21
	v_fmac_f32_e32 v84, v100, v22
	v_fmac_f32_e32 v85, v101, v23
	v_fmac_f32_e32 v86, v102, v24
	v_fmac_f32_e32 v87, v103, v25
	v_mul_f32_e32 v104, 0x3d372713, v88
	v_mul_f32_e32 v105, 0x3d372713, v89
	v_mul_f32_e32 v106, 0x3d372713, v90
	v_mul_f32_e32 v107, 0x3d372713, v91
	v_mul_f32_e32 v108, 0x3d372713, v92
	v_mul_f32_e32 v109, 0x3d372713, v93
	v_mul_f32_e32 v110, 0x3d372713, v94
	v_mul_f32_e32 v111, 0x3d372713, v95
	v_mul_f32_e32 v104, v104, v88
	v_mul_f32_e32 v105, v105, v89
	v_mul_f32_e32 v106, v106, v90
	v_mul_f32_e32 v107, v107, v91
; __device__ __forceinline__ u32x4 pack8(const float (&f)[8]) { u32x4 o; o.x = cvt_pk_bf16(f[0], f[1]); o.y = cvt_pk_bf16(f[2], f[3]); o.z = cvt_pk_bf16(f[4], f[5]); o.w = cvt_pk_bf16(f[6], f[7]); return o; }
; __device__ __forceinline__ float gelu_tanh(float x) { return x * sigmoidf_(1.5957691216057308f * (x + 0.044715f * x * x * x)); }
; __device__ __forceinline__ void fixup_phase(KP p, int l) {
;     ...
;         for (int i = 0; i < 16; ++i) {
;             const size_t m = (size_t)(m0 + i);
;             float hl[8], pc[8], gr[8], o[8], h[8];
;             unpack8(__builtin_nontemporal_load((const u32x4*)(HLOC + m * D + c0)), hl); unpack8(__builtin_nontemporal_load((const u32x4*)(PCUM + m * D + c0)), pc);
;             bf16_t* gp = P + m * DP + C_GR + c0; unpack8(*(const u32x4*)gp, gr);
; #pragma unroll
;             for (int e = 0; e < 8; ++e) { h[e] = hl[e] + pc[e] * carry[e]; o[e] = gelu_tanh(gr[e]) * h[e]; }
;             *(u32x4*)gp = pack8(o);
	v_mul_f32_e32 v108, v108, v92
	v_mul_f32_e32 v109, v109, v93
	v_mul_f32_e32 v110, v110, v94
	v_mul_f32_e32 v111, v111, v95
	v_fma_f32 v104, v104, v88, v88
	v_fma_f32 v105, v105, v89, v89
	v_fma_f32 v106, v106, v90, v90
	v_fma_f32 v107, v107, v91, v91
	v_fma_f32 v108, v108, v92, v92
	v_fma_f32 v109, v109, v93, v93
	v_fma_f32 v110, v110, v94, v94
	v_fma_f32 v111, v111, v95, v95
	v_mul_f32_e32 v104, 0x3fcc422a, v104
	v_mul_f32_e32 v105, 0x3fcc422a, v105
	v_mul_f32_e32 v106, 0x3fcc422a, v106
	v_mul_f32_e32 v107, 0x3fcc422a, v107
	v_mul_f32_e32 v108, 0x3fcc422a, v108
	v_mul_f32_e32 v109, 0x3fcc422a, v109
	v_mul_f32_e32 v110, 0x3fcc422a, v110
	v_mul_f32_e32 v111, 0x3fcc422a, v111
	v_mul_f32_e32 v104, 0xbfb8aa3b, v104
	v_mul_f32_e32 v105, 0xbfb8aa3b, v105
	v_mul_f32_e32 v106, 0xbfb8aa3b, v106
	v_mul_f32_e32 v107, 0xbfb8aa3b, v107
	v_mul_f32_e32 v108, 0xbfb8aa3b, v108
	v_mul_f32_e32 v109, 0xbfb8aa3b, v109
	v_mul_f32_e32 v110, 0xbfb8aa3b, v110
	v_mul_f32_e32 v111, 0xbfb8aa3b, v111
	v_exp_f32_e32 v104, v104
	v_exp_f32_e32 v105, v105
	v_exp_f32_e32 v106, v106
	v_exp_f32_e32 v107, v107
	v_exp_f32_e32 v108, v108
	v_exp_f32_e32 v109, v109
	v_exp_f32_e32 v110, v110
	v_exp_f32_e32 v111, v111
	v_add_f32_e32 v104, 1.0, v104
	v_add_f32_e32 v105, 1.0, v105
	v_add_f32_e32 v106, 1.0, v106
	v_add_f32_e32 v107, 1.0, v107
	v_add_f32_e32 v108, 1.0, v108
	v_add_f32_e32 v109, 1.0, v109
	v_add_f32_e32 v110, 1.0, v110
	v_add_f32_e32 v111, 1.0, v111
	v_rcp_f32_e32 v104, v104
	v_rcp_f32_e32 v105, v105
	v_rcp_f32_e32 v106, v106
	v_rcp_f32_e32 v107, v107
	v_rcp_f32_e32 v108, v108
	v_rcp_f32_e32 v109, v109
	v_rcp_f32_e32 v110, v110
	v_rcp_f32_e32 v111, v111
	v_mul_f32_e32 v104, v104, v88
	v_mul_f32_e32 v105, v105, v89
	v_mul_f32_e32 v106, v106, v90
	v_mul_f32_e32 v107, v107, v91
	v_mul_f32_e32 v108, v108, v92
	v_mul_f32_e32 v109, v109, v93
	v_mul_f32_e32 v110, v110, v94
	v_mul_f32_e32 v111, v111, v95
	v_mul_f32_e32 v104, v80, v104
	v_mul_f32_e32 v105, v81, v105
	v_mul_f32_e32 v106, v82, v106
	v_mul_f32_e32 v107, v83, v107
	v_mul_f32_e32 v108, v84, v108
	v_mul_f32_e32 v109, v85, v109
	v_mul_f32_e32 v110, v86, v110
	v_mul_f32_e32 v111, v87, v111
	v_cvt_pk_bf16_f32 v112, v104, v105
	v_cvt_pk_bf16_f32 v113, v106, v107
	v_cvt_pk_bf16_f32 v114, v108, v109
	v_cvt_pk_bf16_f32 v115, v110, v111
	global_store_dwordx4 v27, v[112:115], s[24:25]
	s_add_u32 s24, s24, 0x2800
	s_addc_u32 s25, s25, 0
	global_load_dwordx4 v[44:47], v31, s[12:13]
	global_load_dwordx4 v[48:51], v31, s[12:13] offset:16
	global_load_dwordx4 v[52:55], v26, s[96:97] nt
	s_add_u32 s12, s12, 0x1000
	s_addc_u32 s13, s13, 0
	s_add_u32 s96, s96, 0x2800
	s_addc_u32 s97, s97, 0
	s_waitcnt vmcnt(12)
	v_lshlrev_b32_e32 v80, 16, v56
	v_and_b32_e32 v96, 0xffff0000, v56
	v_lshlrev_b32_e32 v81, 16, v57
	v_and_b32_e32 v97, 0xffff0000, v57
	v_lshlrev_b32_e32 v82, 16, v58
	v_and_b32_e32 v98, 0xffff0000, v58
	v_lshlrev_b32_e32 v83, 16, v59
	v_and_b32_e32 v99, 0xffff0000, v59
	v_lshlrev_b32_e32 v84, 16, v60
	v_and_b32_e32 v100, 0xffff0000, v60
	v_lshlrev_b32_e32 v85, 16, v61
	v_and_b32_e32 v101, 0xffff0000, v61
	v_lshlrev_b32_e32 v86, 16, v62
	v_and_b32_e32 v102, 0xffff0000, v62
	v_lshlrev_b32_e32 v87, 16, v63
	v_and_b32_e32 v103, 0xffff0000, v63
	v_lshlrev_b32_e32 v88, 16, v64
	v_and_b32_e32 v89, 0xffff0000, v64
	v_lshlrev_b32_e32 v90, 16, v65
	v_and_b32_e32 v91, 0xffff0000, v65
	v_lshlrev_b32_e32 v92, 16, v66
	v_and_b32_e32 v93, 0xffff0000, v66
	v_lshlrev_b32_e32 v94, 16, v67
	v_and_b32_e32 v95, 0xffff0000, v67
	v_fmac_f32_e32 v80, v96, v18
	v_fmac_f32_e32 v81, v97, v19
	v_fmac_f32_e32 v82, v98, v20
	v_fmac_f32_e32 v83, v99, v21
	v_fmac_f32_e32 v84, v100, v22
	v_fmac_f32_e32 v85, v101, v23
	v_fmac_f32_e32 v86, v102, v24
	v_fmac_f32_e32 v87, v103, v25
	v_mul_f32_e32 v104, 0x3d372713, v88
	v_mul_f32_e32 v105, 0x3d372713, v89
	v_mul_f32_e32 v106, 0x3d372713, v90
	v_mul_f32_e32 v107, 0x3d372713, v91
	v_mul_f32_e32 v108, 0x3d372713, v92
	v_mul_f32_e32 v109, 0x3d372713, v93
	v_mul_f32_e32 v110, 0x3d372713, v94
	v_mul_f32_e32 v111, 0x3d372713, v95
	v_mul_f32_e32 v104, v104, v88
	v_mul_f32_e32 v105, v105, v89
	v_mul_f32_e32 v106, v106, v90
	v_mul_f32_e32 v107, v107, v91
	v_mul_f32_e32 v108, v108, v92
	v_mul_f32_e32 v109, v109, v93
	v_mul_f32_e32 v110, v110, v94
	v_mul_f32_e32 v111, v111, v95
	v_fma_f32 v104, v104, v88, v88
	v_fma_f32 v105, v105, v89, v89
	v_fma_f32 v106, v106, v90, v90
	v_fma_f32 v107, v107, v91, v91
	v_fma_f32 v108, v108, v92, v92
	v_fma_f32 v109, v109, v93, v93
	v_fma_f32 v110, v110, v94, v94
	v_fma_f32 v111, v111, v95, v95
	v_mul_f32_e32 v104, 0x3fcc422a, v104
	v_mul_f32_e32 v105, 0x3fcc422a, v105
	v_mul_f32_e32 v106, 0x3fcc422a, v106
	v_mul_f32_e32 v107, 0x3fcc422a, v107
	v_mul_f32_e32 v108, 0x3fcc422a, v108
	v_mul_f32_e32 v109, 0x3fcc422a, v109
	v_mul_f32_e32 v110, 0x3fcc422a, v110
	v_mul_f32_e32 v111, 0x3fcc422a, v111
	v_mul_f32_e32 v104, 0xbfb8aa3b, v104
	v_mul_f32_e32 v105, 0xbfb8aa3b, v105
	v_mul_f32_e32 v106, 0xbfb8aa3b, v106
	v_mul_f32_e32 v107, 0xbfb8aa3b, v107
	v_mul_f32_e32 v108, 0xbfb8aa3b, v108
	v_mul_f32_e32 v109, 0xbfb8aa3b, v109
	v_mul_f32_e32 v110, 0xbfb8aa3b, v110
	v_mul_f32_e32 v111, 0xbfb8aa3b, v111
	v_exp_f32_e32 v104, v104
	v_exp_f32_e32 v105, v105
	v_exp_f32_e32 v106, v106
	v_exp_f32_e32 v107, v107
	v_exp_f32_e32 v108, v108
	v_exp_f32_e32 v109, v109
	v_exp_f32_e32 v110, v110
	v_exp_f32_e32 v111, v111
	v_add_f32_e32 v104, 1.0, v104
	v_add_f32_e32 v105, 1.0, v105
	v_add_f32_e32 v106, 1.0, v106
	v_add_f32_e32 v107, 1.0, v107
	v_add_f32_e32 v108, 1.0, v108
	v_add_f32_e32 v109, 1.0, v109
	v_add_f32_e32 v110, 1.0, v110
	v_add_f32_e32 v111, 1.0, v111
	v_rcp_f32_e32 v104, v104
	v_rcp_f32_e32 v105, v105
	v_rcp_f32_e32 v106, v106
	v_rcp_f32_e32 v107, v107
	v_rcp_f32_e32 v108, v108
	v_rcp_f32_e32 v109, v109
	v_rcp_f32_e32 v110, v110
	v_rcp_f32_e32 v111, v111
	v_mul_f32_e32 v104, v104, v88
	v_mul_f32_e32 v105, v105, v89
	v_mul_f32_e32 v106, v106, v90
	v_mul_f32_e32 v107, v107, v91
	v_mul_f32_e32 v108, v108, v92
	v_mul_f32_e32 v109, v109, v93
	v_mul_f32_e32 v110, v110, v94
	v_mul_f32_e32 v111, v111, v95
	v_mul_f32_e32 v104, v80, v104
	v_mul_f32_e32 v105, v81, v105
	v_mul_f32_e32 v106, v82, v106
	v_mul_f32_e32 v107, v83, v107
	v_mul_f32_e32 v108, v84, v108
	v_mul_f32_e32 v109, v85, v109
	v_mul_f32_e32 v110, v86, v110
	v_mul_f32_e32 v111, v87, v111
	v_cvt_pk_bf16_f32 v112, v104, v105
	v_cvt_pk_bf16_f32 v113, v106, v107
	v_cvt_pk_bf16_f32 v114, v108, v109
	v_cvt_pk_bf16_f32 v115, v110, v111
	global_store_dwordx4 v27, v[112:115], s[24:25]
	s_add_u32 s24, s24, 0x2800
	s_addc_u32 s25, s25, 0
	global_load_dwordx4 v[56:59], v31, s[12:13]
	global_load_dwordx4 v[60:63], v31, s[12:13] offset:16
	global_load_dwordx4 v[64:67], v26, s[96:97] nt
	s_add_u32 s12, s12, 0x1000
	s_addc_u32 s13, s13, 0
	s_add_u32 s96, s96, 0x2800
	s_addc_u32 s97, s97, 0
	s_waitcnt vmcnt(12)
; __device__ __forceinline__ u32x4 pack8(const float (&f)[8]) { u32x4 o; o.x = cvt_pk_bf16(f[0], f[1]); o.y = cvt_pk_bf16(f[2], f[3]); o.z = cvt_pk_bf16(f[4], f[5]); o.w = cvt_pk_bf16(f[6], f[7]); return o; }
; __device__ __forceinline__ float gelu_tanh(float x) { return x * sigmoidf_(1.5957691216057308f * (x + 0.044715f * x * x * x)); }
; __device__ __forceinline__ void fixup_phase(KP p, int l) {
;     ...
;         for (int i = 0; i < 16; ++i) {
;             const size_t m = (size_t)(m0 + i);
;             float hl[8], pc[8], gr[8], o[8], h[8];
;             unpack8(__builtin_nontemporal_load((const u32x4*)(HLOC + m * D + c0)), hl); unpack8(__builtin_nontemporal_load((const u32x4*)(PCUM + m * D + c0)), pc);
;             bf16_t* gp = P + m * DP + C_GR + c0; unpack8(*(const u32x4*)gp, gr);
; #pragma unroll
;             for (int e = 0; e < 8; ++e) { h[e] = hl[e] + pc[e] * carry[e]; o[e] = gelu_tanh(gr[e]) * h[e]; }
;             *(u32x4*)gp = pack8(o);
	v_lshlrev_b32_e32 v80, 16, v68
	v_and_b32_e32 v96, 0xffff0000, v68
	v_lshlrev_b32_e32 v81, 16, v69
	v_and_b32_e32 v97, 0xffff0000, v69
	v_lshlrev_b32_e32 v82, 16, v70
	v_and_b32_e32 v98, 0xffff0000, v70
	v_lshlrev_b32_e32 v83, 16, v71
	v_and_b32_e32 v99, 0xffff0000, v71
	v_lshlrev_b32_e32 v84, 16, v72
	v_and_b32_e32 v100, 0xffff0000, v72
	v_lshlrev_b32_e32 v85, 16, v73
	v_and_b32_e32 v101, 0xffff0000, v73
	v_lshlrev_b32_e32 v86, 16, v74
	v_and_b32_e32 v102, 0xffff0000, v74
	v_lshlrev_b32_e32 v87, 16, v75
	v_and_b32_e32 v103, 0xffff0000, v75
	v_lshlrev_b32_e32 v88, 16, v76
	v_and_b32_e32 v89, 0xffff0000, v76
	v_lshlrev_b32_e32 v90, 16, v77
	v_and_b32_e32 v91, 0xffff0000, v77
	v_lshlrev_b32_e32 v92, 16, v78
	v_and_b32_e32 v93, 0xffff0000, v78
	v_lshlrev_b32_e32 v94, 16, v79
	v_and_b32_e32 v95, 0xffff0000, v79
	v_fmac_f32_e32 v80, v96, v18
	v_fmac_f32_e32 v81, v97, v19
	v_fmac_f32_e32 v82, v98, v20
	v_fmac_f32_e32 v83, v99, v21
	v_fmac_f32_e32 v84, v100, v22
	v_fmac_f32_e32 v85, v101, v23
	v_fmac_f32_e32 v86, v102, v24
	v_fmac_f32_e32 v87, v103, v25
	v_mul_f32_e32 v104, 0x3d372713, v88
	v_mul_f32_e32 v105, 0x3d372713, v89
	v_mul_f32_e32 v106, 0x3d372713, v90
	v_mul_f32_e32 v107, 0x3d372713, v91
	v_mul_f32_e32 v108, 0x3d372713, v92
	v_mul_f32_e32 v109, 0x3d372713, v93
	v_mul_f32_e32 v110, 0x3d372713, v94
	v_mul_f32_e32 v111, 0x3d372713, v95
	v_mul_f32_e32 v104, v104, v88
	v_mul_f32_e32 v105, v105, v89
	v_mul_f32_e32 v106, v106, v90
	v_mul_f32_e32 v107, v107, v91
	v_mul_f32_e32 v108, v108, v92
	v_mul_f32_e32 v109, v109, v93
	v_mul_f32_e32 v110, v110, v94
	v_mul_f32_e32 v111, v111, v95
	v_fma_f32 v104, v104, v88, v88
	v_fma_f32 v105, v105, v89, v89
	v_fma_f32 v106, v106, v90, v90
	v_fma_f32 v107, v107, v91, v91
	v_fma_f32 v108, v108, v92, v92
	v_fma_f32 v109, v109, v93, v93
	v_fma_f32 v110, v110, v94, v94
	v_fma_f32 v111, v111, v95, v95
	v_mul_f32_e32 v104, 0x3fcc422a, v104
	v_mul_f32_e32 v105, 0x3fcc422a, v105
	v_mul_f32_e32 v106, 0x3fcc422a, v106
	v_mul_f32_e32 v107, 0x3fcc422a, v107
	v_mul_f32_e32 v108, 0x3fcc422a, v108
	v_mul_f32_e32 v109, 0x3fcc422a, v109
	v_mul_f32_e32 v110, 0x3fcc422a, v110
	v_mul_f32_e32 v111, 0x3fcc422a, v111
	v_mul_f32_e32 v104, 0xbfb8aa3b, v104
	v_mul_f32_e32 v105, 0xbfb8aa3b, v105
	v_mul_f32_e32 v106, 0xbfb8aa3b, v106
	v_mul_f32_e32 v107, 0xbfb8aa3b, v107
	v_mul_f32_e32 v108, 0xbfb8aa3b, v108
	v_mul_f32_e32 v109, 0xbfb8aa3b, v109
	v_mul_f32_e32 v110, 0xbfb8aa3b, v110
	v_mul_f32_e32 v111, 0xbfb8aa3b, v111
	v_exp_f32_e32 v104, v104
	v_exp_f32_e32 v105, v105
	v_exp_f32_e32 v106, v106
	v_exp_f32_e32 v107, v107
	v_exp_f32_e32 v108, v108
	v_exp_f32_e32 v109, v109
	v_exp_f32_e32 v110, v110
	v_exp_f32_e32 v111, v111
	v_add_f32_e32 v104, 1.0, v104
	v_add_f32_e32 v105, 1.0, v105
	v_add_f32_e32 v106, 1.0, v106
	v_add_f32_e32 v107, 1.0, v107
	v_add_f32_e32 v108, 1.0, v108
	v_add_f32_e32 v109, 1.0, v109
	v_add_f32_e32 v110, 1.0, v110
	v_add_f32_e32 v111, 1.0, v111
	v_rcp_f32_e32 v104, v104
	v_rcp_f32_e32 v105, v105
	v_rcp_f32_e32 v106, v106
	v_rcp_f32_e32 v107, v107
	v_rcp_f32_e32 v108, v108
	v_rcp_f32_e32 v109, v109
	v_rcp_f32_e32 v110, v110
	v_rcp_f32_e32 v111, v111
	v_mul_f32_e32 v104, v104, v88
	v_mul_f32_e32 v105, v105, v89
	v_mul_f32_e32 v106, v106, v90
	v_mul_f32_e32 v107, v107, v91
	v_mul_f32_e32 v108, v108, v92
	v_mul_f32_e32 v109, v109, v93
	v_mul_f32_e32 v110, v110, v94
	v_mul_f32_e32 v111, v111, v95
	v_mul_f32_e32 v104, v80, v104
	v_mul_f32_e32 v105, v81, v105
	v_mul_f32_e32 v106, v82, v106
	v_mul_f32_e32 v107, v83, v107
	v_mul_f32_e32 v108, v84, v108
	v_mul_f32_e32 v109, v85, v109
	v_mul_f32_e32 v110, v86, v110
	v_mul_f32_e32 v111, v87, v111
	v_cvt_pk_bf16_f32 v112, v104, v105
	v_cvt_pk_bf16_f32 v113, v106, v107
	v_cvt_pk_bf16_f32 v114, v108, v109
	v_cvt_pk_bf16_f32 v115, v110, v111
	global_store_dwordx4 v27, v[112:115], s[24:25]
	s_add_u32 s24, s24, 0x2800
	s_addc_u32 s25, s25, 0
	global_load_dwordx4 v[68:71], v31, s[12:13]
	global_load_dwordx4 v[72:75], v31, s[12:13] offset:16
	global_load_dwordx4 v[76:79], v26, s[96:97] nt
	s_add_u32 s12, s12, 0x1000
	s_addc_u32 s13, s13, 0
	s_add_u32 s96, s96, 0x2800
	s_addc_u32 s97, s97, 0
	s_waitcnt vmcnt(12)
	v_lshlrev_b32_e32 v80, 16, v32
	v_and_b32_e32 v96, 0xffff0000, v32
	v_lshlrev_b32_e32 v81, 16, v33
	v_and_b32_e32 v97, 0xffff0000, v33
	v_lshlrev_b32_e32 v82, 16, v34
	v_and_b32_e32 v98, 0xffff0000, v34
	v_lshlrev_b32_e32 v83, 16, v35
	v_and_b32_e32 v99, 0xffff0000, v35
	v_lshlrev_b32_e32 v84, 16, v36
	v_and_b32_e32 v100, 0xffff0000, v36
	v_lshlrev_b32_e32 v85, 16, v37
	v_and_b32_e32 v101, 0xffff0000, v37
	v_lshlrev_b32_e32 v86, 16, v38
	v_and_b32_e32 v102, 0xffff0000, v38
	v_lshlrev_b32_e32 v87, 16, v39
	v_and_b32_e32 v103, 0xffff0000, v39
	v_lshlrev_b32_e32 v88, 16, v40
	v_and_b32_e32 v89, 0xffff0000, v40
	v_lshlrev_b32_e32 v90, 16, v41
	v_and_b32_e32 v91, 0xffff0000, v41
	v_lshlrev_b32_e32 v92, 16, v42
	v_and_b32_e32 v93, 0xffff0000, v42
	v_lshlrev_b32_e32 v94, 16, v43
	v_and_b32_e32 v95, 0xffff0000, v43
	v_fmac_f32_e32 v80, v96, v18
	v_fmac_f32_e32 v81, v97, v19
	v_fmac_f32_e32 v82, v98, v20
	v_fmac_f32_e32 v83, v99, v21
	v_fmac_f32_e32 v84, v100, v22
	v_fmac_f32_e32 v85, v101, v23
	v_fmac_f32_e32 v86, v102, v24
	v_fmac_f32_e32 v87, v103, v25
	v_mul_f32_e32 v104, 0x3d372713, v88
	v_mul_f32_e32 v105, 0x3d372713, v89
	v_mul_f32_e32 v106, 0x3d372713, v90
	v_mul_f32_e32 v107, 0x3d372713, v91
	v_mul_f32_e32 v108, 0x3d372713, v92
	v_mul_f32_e32 v109, 0x3d372713, v93
	v_mul_f32_e32 v110, 0x3d372713, v94
	v_mul_f32_e32 v111, 0x3d372713, v95
	v_mul_f32_e32 v104, v104, v88
	v_mul_f32_e32 v105, v105, v89
	v_mul_f32_e32 v106, v106, v90
	v_mul_f32_e32 v107, v107, v91
; __device__ __forceinline__ u32x4 pack8(const float (&f)[8]) { u32x4 o; o.x = cvt_pk_bf16(f[0], f[1]); o.y = cvt_pk_bf16(f[2], f[3]); o.z = cvt_pk_bf16(f[4], f[5]); o.w = cvt_pk_bf16(f[6], f[7]); return o; }
; __device__ __forceinline__ float gelu_tanh(float x) { return x * sigmoidf_(1.5957691216057308f * (x + 0.044715f * x * x * x)); }
; __device__ __forceinline__ void fixup_phase(KP p, int l) {
;     ...
;         for (int i = 0; i < 16; ++i) {
;             const size_t m = (size_t)(m0 + i);
;             float hl[8], pc[8], gr[8], o[8], h[8];
;             unpack8(__builtin_nontemporal_load((const u32x4*)(HLOC + m * D + c0)), hl); unpack8(__builtin_nontemporal_load((const u32x4*)(PCUM + m * D + c0)), pc);
;             bf16_t* gp = P + m * DP + C_GR + c0; unpack8(*(const u32x4*)gp, gr);
; #pragma unroll
;             for (int e = 0; e < 8; ++e) { h[e] = hl[e] + pc[e] * carry[e]; o[e] = gelu_tanh(gr[e]) * h[e]; }
;             *(u32x4*)gp = pack8(o);
	v_mul_f32_e32 v108, v108, v92
	v_mul_f32_e32 v109, v109, v93
	v_mul_f32_e32 v110, v110, v94
	v_mul_f32_e32 v111, v111, v95
	v_fma_f32 v104, v104, v88, v88
	v_fma_f32 v105, v105, v89, v89
	v_fma_f32 v106, v106, v90, v90
	v_fma_f32 v107, v107, v91, v91
	v_fma_f32 v108, v108, v92, v92
	v_fma_f32 v109, v109, v93, v93
	v_fma_f32 v110, v110, v94, v94
	v_fma_f32 v111, v111, v95, v95
	v_mul_f32_e32 v104, 0x3fcc422a, v104
	v_mul_f32_e32 v105, 0x3fcc422a, v105
	v_mul_f32_e32 v106, 0x3fcc422a, v106
	v_mul_f32_e32 v107, 0x3fcc422a, v107
	v_mul_f32_e32 v108, 0x3fcc422a, v108
	v_mul_f32_e32 v109, 0x3fcc422a, v109
	v_mul_f32_e32 v110, 0x3fcc422a, v110
	v_mul_f32_e32 v111, 0x3fcc422a, v111
	v_mul_f32_e32 v104, 0xbfb8aa3b, v104
	v_mul_f32_e32 v105, 0xbfb8aa3b, v105
	v_mul_f32_e32 v106, 0xbfb8aa3b, v106
	v_mul_f32_e32 v107, 0xbfb8aa3b, v107
	v_mul_f32_e32 v108, 0xbfb8aa3b, v108
	v_mul_f32_e32 v109, 0xbfb8aa3b, v109
	v_mul_f32_e32 v110, 0xbfb8aa3b, v110
	v_mul_f32_e32 v111, 0xbfb8aa3b, v111
	v_exp_f32_e32 v104, v104
	v_exp_f32_e32 v105, v105
	v_exp_f32_e32 v106, v106
	v_exp_f32_e32 v107, v107
	v_exp_f32_e32 v108, v108
	v_exp_f32_e32 v109, v109
	v_exp_f32_e32 v110, v110
	v_exp_f32_e32 v111, v111
	v_add_f32_e32 v104, 1.0, v104
	v_add_f32_e32 v105, 1.0, v105
	v_add_f32_e32 v106, 1.0, v106
	v_add_f32_e32 v107, 1.0, v107
	v_add_f32_e32 v108, 1.0, v108
	v_add_f32_e32 v109, 1.0, v109
	v_add_f32_e32 v110, 1.0, v110
	v_add_f32_e32 v111, 1.0, v111
	v_rcp_f32_e32 v104, v104
	v_rcp_f32_e32 v105, v105
	v_rcp_f32_e32 v106, v106
	v_rcp_f32_e32 v107, v107
	v_rcp_f32_e32 v108, v108
	v_rcp_f32_e32 v109, v109
	v_rcp_f32_e32 v110, v110
	v_rcp_f32_e32 v111, v111
	v_mul_f32_e32 v104, v104, v88
	v_mul_f32_e32 v105, v105, v89
	v_mul_f32_e32 v106, v106, v90
	v_mul_f32_e32 v107, v107, v91
	v_mul_f32_e32 v108, v108, v92
	v_mul_f32_e32 v109, v109, v93
	v_mul_f32_e32 v110, v110, v94
	v_mul_f32_e32 v111, v111, v95
	v_mul_f32_e32 v104, v80, v104
	v_mul_f32_e32 v105, v81, v105
	v_mul_f32_e32 v106, v82, v106
	v_mul_f32_e32 v107, v83, v107
	v_mul_f32_e32 v108, v84, v108
	v_mul_f32_e32 v109, v85, v109
	v_mul_f32_e32 v110, v86, v110
	v_mul_f32_e32 v111, v87, v111
	v_cvt_pk_bf16_f32 v112, v104, v105
	v_cvt_pk_bf16_f32 v113, v106, v107
	v_cvt_pk_bf16_f32 v114, v108, v109
	v_cvt_pk_bf16_f32 v115, v110, v111
	global_store_dwordx4 v27, v[112:115], s[24:25]
	s_add_u32 s24, s24, 0x2800
	s_addc_u32 s25, s25, 0
	global_load_dwordx4 v[32:35], v31, s[12:13]
	global_load_dwordx4 v[36:39], v31, s[12:13] offset:16
	global_load_dwordx4 v[40:43], v26, s[96:97] nt
	s_add_u32 s12, s12, 0x1000
	s_addc_u32 s13, s13, 0
	s_add_u32 s96, s96, 0x2800
	s_addc_u32 s97, s97, 0
	s_waitcnt vmcnt(12)
	v_lshlrev_b32_e32 v80, 16, v44
	v_and_b32_e32 v96, 0xffff0000, v44
	v_lshlrev_b32_e32 v81, 16, v45
	v_and_b32_e32 v97, 0xffff0000, v45
	v_lshlrev_b32_e32 v82, 16, v46
	v_and_b32_e32 v98, 0xffff0000, v46
	v_lshlrev_b32_e32 v83, 16, v47
	v_and_b32_e32 v99, 0xffff0000, v47
	v_lshlrev_b32_e32 v84, 16, v48
	v_and_b32_e32 v100, 0xffff0000, v48
	v_lshlrev_b32_e32 v85, 16, v49
	v_and_b32_e32 v101, 0xffff0000, v49
	v_lshlrev_b32_e32 v86, 16, v50
	v_and_b32_e32 v102, 0xffff0000, v50
	v_lshlrev_b32_e32 v87, 16, v51
	v_and_b32_e32 v103, 0xffff0000, v51
	v_lshlrev_b32_e32 v88, 16, v52
	v_and_b32_e32 v89, 0xffff0000, v52
	v_lshlrev_b32_e32 v90, 16, v53
	v_and_b32_e32 v91, 0xffff0000, v53
	v_lshlrev_b32_e32 v92, 16, v54
	v_and_b32_e32 v93, 0xffff0000, v54
	v_lshlrev_b32_e32 v94, 16, v55
	v_and_b32_e32 v95, 0xffff0000, v55
	v_fmac_f32_e32 v80, v96, v18
	v_fmac_f32_e32 v81, v97, v19
	v_fmac_f32_e32 v82, v98, v20
	v_fmac_f32_e32 v83, v99, v21
	v_fmac_f32_e32 v84, v100, v22
	v_fmac_f32_e32 v85, v101, v23
	v_fmac_f32_e32 v86, v102, v24
	v_fmac_f32_e32 v87, v103, v25
	v_mul_f32_e32 v104, 0x3d372713, v88
	v_mul_f32_e32 v105, 0x3d372713, v89
	v_mul_f32_e32 v106, 0x3d372713, v90
	v_mul_f32_e32 v107, 0x3d372713, v91
	v_mul_f32_e32 v108, 0x3d372713, v92
	v_mul_f32_e32 v109, 0x3d372713, v93
	v_mul_f32_e32 v110, 0x3d372713, v94
	v_mul_f32_e32 v111, 0x3d372713, v95
	v_mul_f32_e32 v104, v104, v88
	v_mul_f32_e32 v105, v105, v89
	v_mul_f32_e32 v106, v106, v90
	v_mul_f32_e32 v107, v107, v91
	v_mul_f32_e32 v108, v108, v92
	v_mul_f32_e32 v109, v109, v93
	v_mul_f32_e32 v110, v110, v94
	v_mul_f32_e32 v111, v111, v95
	v_fma_f32 v104, v104, v88, v88
	v_fma_f32 v105, v105, v89, v89
	v_fma_f32 v106, v106, v90, v90
	v_fma_f32 v107, v107, v91, v91
	v_fma_f32 v108, v108, v92, v92
	v_fma_f32 v109, v109, v93, v93
	v_fma_f32 v110, v110, v94, v94
	v_fma_f32 v111, v111, v95, v95
	v_mul_f32_e32 v104, 0x3fcc422a, v104
	v_mul_f32_e32 v105, 0x3fcc422a, v105
	v_mul_f32_e32 v106, 0x3fcc422a, v106
	v_mul_f32_e32 v107, 0x3fcc422a, v107
	v_mul_f32_e32 v108, 0x3fcc422a, v108
	v_mul_f32_e32 v109, 0x3fcc422a, v109
	v_mul_f32_e32 v110, 0x3fcc422a, v110
	v_mul_f32_e32 v111, 0x3fcc422a, v111
	v_mul_f32_e32 v104, 0xbfb8aa3b, v104
	v_mul_f32_e32 v105, 0xbfb8aa3b, v105
	v_mul_f32_e32 v106, 0xbfb8aa3b, v106
	v_mul_f32_e32 v107, 0xbfb8aa3b, v107
	v_mul_f32_e32 v108, 0xbfb8aa3b, v108
	v_mul_f32_e32 v109, 0xbfb8aa3b, v109
	v_mul_f32_e32 v110, 0xbfb8aa3b, v110
	v_mul_f32_e32 v111, 0xbfb8aa3b, v111
	v_exp_f32_e32 v104, v104
	v_exp_f32_e32 v105, v105
	v_exp_f32_e32 v106, v106
	v_exp_f32_e32 v107, v107
	v_exp_f32_e32 v108, v108
	v_exp_f32_e32 v109, v109
	v_exp_f32_e32 v110, v110
	v_exp_f32_e32 v111, v111
	v_add_f32_e32 v104, 1.0, v104
	v_add_f32_e32 v105, 1.0, v105
	v_add_f32_e32 v106, 1.0, v106
	v_add_f32_e32 v107, 1.0, v107
	v_add_f32_e32 v108, 1.0, v108
	v_add_f32_e32 v109, 1.0, v109
	v_add_f32_e32 v110, 1.0, v110
	v_add_f32_e32 v111, 1.0, v111
	v_rcp_f32_e32 v104, v104
	v_rcp_f32_e32 v105, v105
	v_rcp_f32_e32 v106, v106
	v_rcp_f32_e32 v107, v107
	v_rcp_f32_e32 v108, v108
	v_rcp_f32_e32 v109, v109
	v_rcp_f32_e32 v110, v110
	v_rcp_f32_e32 v111, v111
	v_mul_f32_e32 v104, v104, v88
	v_mul_f32_e32 v105, v105, v89
	v_mul_f32_e32 v106, v106, v90
	v_mul_f32_e32 v107, v107, v91
	v_mul_f32_e32 v108, v108, v92
	v_mul_f32_e32 v109, v109, v93
	v_mul_f32_e32 v110, v110, v94
	v_mul_f32_e32 v111, v111, v95
	v_mul_f32_e32 v104, v80, v104
	v_mul_f32_e32 v105, v81, v105
	v_mul_f32_e32 v106, v82, v106
	v_mul_f32_e32 v107, v83, v107
	v_mul_f32_e32 v108, v84, v108
	v_mul_f32_e32 v109, v85, v109
	v_mul_f32_e32 v110, v86, v110
	v_mul_f32_e32 v111, v87, v111
	v_cvt_pk_bf16_f32 v112, v104, v105
	v_cvt_pk_bf16_f32 v113, v106, v107
	v_cvt_pk_bf16_f32 v114, v108, v109
	v_cvt_pk_bf16_f32 v115, v110, v111
	global_store_dwordx4 v27, v[112:115], s[24:25]
	s_add_u32 s24, s24, 0x2800
	s_addc_u32 s25, s25, 0
	global_load_dwordx4 v[44:47], v31, s[12:13]
	global_load_dwordx4 v[48:51], v31, s[12:13] offset:16
	global_load_dwordx4 v[52:55], v26, s[96:97] nt
	s_add_u32 s12, s12, 0x1000
	s_addc_u32 s13, s13, 0
	s_add_u32 s96, s96, 0x2800
	s_addc_u32 s97, s97, 0
	s_waitcnt vmcnt(12)
; __device__ __forceinline__ u32x4 pack8(const float (&f)[8]) { u32x4 o; o.x = cvt_pk_bf16(f[0], f[1]); o.y = cvt_pk_bf16(f[2], f[3]); o.z = cvt_pk_bf16(f[4], f[5]); o.w = cvt_pk_bf16(f[6], f[7]); return o; }
; __device__ __forceinline__ float gelu_tanh(float x) { return x * sigmoidf_(1.5957691216057308f * (x + 0.044715f * x * x * x)); }
; __device__ __forceinline__ void fixup_phase(KP p, int l) {
;     ...
;         for (int i = 0; i < 16; ++i) {
;             const size_t m = (size_t)(m0 + i);
;             float hl[8], pc[8], gr[8], o[8], h[8];
;             unpack8(__builtin_nontemporal_load((const u32x4*)(HLOC + m * D + c0)), hl); unpack8(__builtin_nontemporal_load((const u32x4*)(PCUM + m * D + c0)), pc);
;             bf16_t* gp = P + m * DP + C_GR + c0; unpack8(*(const u32x4*)gp, gr);
; #pragma unroll
;             for (int e = 0; e < 8; ++e) { h[e] = hl[e] + pc[e] * carry[e]; o[e] = gelu_tanh(gr[e]) * h[e]; }
;             *(u32x4*)gp = pack8(o);
	v_lshlrev_b32_e32 v80, 16, v56
	v_and_b32_e32 v96, 0xffff0000, v56
	v_lshlrev_b32_e32 v81, 16, v57
	v_and_b32_e32 v97, 0xffff0000, v57
	v_lshlrev_b32_e32 v82, 16, v58
	v_and_b32_e32 v98, 0xffff0000, v58
	v_lshlrev_b32_e32 v83, 16, v59
	v_and_b32_e32 v99, 0xffff0000, v59
	v_lshlrev_b32_e32 v84, 16, v60
	v_and_b32_e32 v100, 0xffff0000, v60
	v_lshlrev_b32_e32 v85, 16, v61
	v_and_b32_e32 v101, 0xffff0000, v61
	v_lshlrev_b32_e32 v86, 16, v62
	v_and_b32_e32 v102, 0xffff0000, v62
	v_lshlrev_b32_e32 v87, 16, v63
	v_and_b32_e32 v103, 0xffff0000, v63
	v_lshlrev_b32_e32 v88, 16, v64
	v_and_b32_e32 v89, 0xffff0000, v64
	v_lshlrev_b32_e32 v90, 16, v65
	v_and_b32_e32 v91, 0xffff0000, v65
	v_lshlrev_b32_e32 v92, 16, v66
	v_and_b32_e32 v93, 0xffff0000, v66
	v_lshlrev_b32_e32 v94, 16, v67
	v_and_b32_e32 v95, 0xffff0000, v67
	v_fmac_f32_e32 v80, v96, v18
	v_fmac_f32_e32 v81, v97, v19
	v_fmac_f32_e32 v82, v98, v20
	v_fmac_f32_e32 v83, v99, v21
	v_fmac_f32_e32 v84, v100, v22
	v_fmac_f32_e32 v85, v101, v23
	v_fmac_f32_e32 v86, v102, v24
	v_fmac_f32_e32 v87, v103, v25
	v_mul_f32_e32 v104, 0x3d372713, v88
	v_mul_f32_e32 v105, 0x3d372713, v89
	v_mul_f32_e32 v106, 0x3d372713, v90
	v_mul_f32_e32 v107, 0x3d372713, v91
	v_mul_f32_e32 v108, 0x3d372713, v92
	v_mul_f32_e32 v109, 0x3d372713, v93
	v_mul_f32_e32 v110, 0x3d372713, v94
	v_mul_f32_e32 v111, 0x3d372713, v95
	v_mul_f32_e32 v104, v104, v88
	v_mul_f32_e32 v105, v105, v89
	v_mul_f32_e32 v106, v106, v90
	v_mul_f32_e32 v107, v107, v91
	v_mul_f32_e32 v108, v108, v92
	v_mul_f32_e32 v109, v109, v93
	v_mul_f32_e32 v110, v110, v94
	v_mul_f32_e32 v111, v111, v95
	v_fma_f32 v104, v104, v88, v88
	v_fma_f32 v105, v105, v89, v89
	v_fma_f32 v106, v106, v90, v90
	v_fma_f32 v107, v107, v91, v91
	v_fma_f32 v108, v108, v92, v92
	v_fma_f32 v109, v109, v93, v93
	v_fma_f32 v110, v110, v94, v94
	v_fma_f32 v111, v111, v95, v95
	v_mul_f32_e32 v104, 0x3fcc422a, v104
	v_mul_f32_e32 v105, 0x3fcc422a, v105
	v_mul_f32_e32 v106, 0x3fcc422a, v106
	v_mul_f32_e32 v107, 0x3fcc422a, v107
	v_mul_f32_e32 v108, 0x3fcc422a, v108
	v_mul_f32_e32 v109, 0x3fcc422a, v109
	v_mul_f32_e32 v110, 0x3fcc422a, v110
	v_mul_f32_e32 v111, 0x3fcc422a, v111
	v_mul_f32_e32 v104, 0xbfb8aa3b, v104
	v_mul_f32_e32 v105, 0xbfb8aa3b, v105
	v_mul_f32_e32 v106, 0xbfb8aa3b, v106
	v_mul_f32_e32 v107, 0xbfb8aa3b, v107
	v_mul_f32_e32 v108, 0xbfb8aa3b, v108
	v_mul_f32_e32 v109, 0xbfb8aa3b, v109
	v_mul_f32_e32 v110, 0xbfb8aa3b, v110
	v_mul_f32_e32 v111, 0xbfb8aa3b, v111
	v_exp_f32_e32 v104, v104
	v_exp_f32_e32 v105, v105
	v_exp_f32_e32 v106, v106
	v_exp_f32_e32 v107, v107
	v_exp_f32_e32 v108, v108
	v_exp_f32_e32 v109, v109
	v_exp_f32_e32 v110, v110
	v_exp_f32_e32 v111, v111
	v_add_f32_e32 v104, 1.0, v104
	v_add_f32_e32 v105, 1.0, v105
	v_add_f32_e32 v106, 1.0, v106
	v_add_f32_e32 v107, 1.0, v107
	v_add_f32_e32 v108, 1.0, v108
	v_add_f32_e32 v109, 1.0, v109
	v_add_f32_e32 v110, 1.0, v110
	v_add_f32_e32 v111, 1.0, v111
	v_rcp_f32_e32 v104, v104
	v_rcp_f32_e32 v105, v105
	v_rcp_f32_e32 v106, v106
	v_rcp_f32_e32 v107, v107
	v_rcp_f32_e32 v108, v108
	v_rcp_f32_e32 v109, v109
	v_rcp_f32_e32 v110, v110
	v_rcp_f32_e32 v111, v111
	v_mul_f32_e32 v104, v104, v88
	v_mul_f32_e32 v105, v105, v89
	v_mul_f32_e32 v106, v106, v90
	v_mul_f32_e32 v107, v107, v91
	v_mul_f32_e32 v108, v108, v92
	v_mul_f32_e32 v109, v109, v93
	v_mul_f32_e32 v110, v110, v94
	v_mul_f32_e32 v111, v111, v95
	v_mul_f32_e32 v104, v80, v104
	v_mul_f32_e32 v105, v81, v105
	v_mul_f32_e32 v106, v82, v106
	v_mul_f32_e32 v107, v83, v107
	v_mul_f32_e32 v108, v84, v108
	v_mul_f32_e32 v109, v85, v109
	v_mul_f32_e32 v110, v86, v110
	v_mul_f32_e32 v111, v87, v111
	v_cvt_pk_bf16_f32 v112, v104, v105
	v_cvt_pk_bf16_f32 v113, v106, v107
	v_cvt_pk_bf16_f32 v114, v108, v109
	v_cvt_pk_bf16_f32 v115, v110, v111
	global_store_dwordx4 v27, v[112:115], s[24:25]
	s_add_u32 s24, s24, 0x2800
	s_addc_u32 s25, s25, 0
	global_load_dwordx4 v[56:59], v31, s[12:13]
	global_load_dwordx4 v[60:63], v31, s[12:13] offset:16
	global_load_dwordx4 v[64:67], v26, s[96:97] nt
	s_add_u32 s12, s12, 0x1000
	s_addc_u32 s13, s13, 0
	s_add_u32 s96, s96, 0x2800
	s_addc_u32 s97, s97, 0
	s_waitcnt vmcnt(12)
	v_lshlrev_b32_e32 v80, 16, v68
	v_and_b32_e32 v96, 0xffff0000, v68
	v_lshlrev_b32_e32 v81, 16, v69
	v_and_b32_e32 v97, 0xffff0000, v69
	v_lshlrev_b32_e32 v82, 16, v70
	v_and_b32_e32 v98, 0xffff0000, v70
	v_lshlrev_b32_e32 v83, 16, v71
	v_and_b32_e32 v99, 0xffff0000, v71
	v_lshlrev_b32_e32 v84, 16, v72
	v_and_b32_e32 v100, 0xffff0000, v72
	v_lshlrev_b32_e32 v85, 16, v73
	v_and_b32_e32 v101, 0xffff0000, v73
	v_lshlrev_b32_e32 v86, 16, v74
	v_and_b32_e32 v102, 0xffff0000, v74
	v_lshlrev_b32_e32 v87, 16, v75
	v_and_b32_e32 v103, 0xffff0000, v75
	v_lshlrev_b32_e32 v88, 16, v76
	v_and_b32_e32 v89, 0xffff0000, v76
	v_lshlrev_b32_e32 v90, 16, v77
	v_and_b32_e32 v91, 0xffff0000, v77
	v_lshlrev_b32_e32 v92, 16, v78
	v_and_b32_e32 v93, 0xffff0000, v78
	v_lshlrev_b32_e32 v94, 16, v79
	v_and_b32_e32 v95, 0xffff0000, v79
	v_fmac_f32_e32 v80, v96, v18
	v_fmac_f32_e32 v81, v97, v19
	v_fmac_f32_e32 v82, v98, v20
	v_fmac_f32_e32 v83, v99, v21
	v_fmac_f32_e32 v84, v100, v22
	v_fmac_f32_e32 v85, v101, v23
	v_fmac_f32_e32 v86, v102, v24
	v_fmac_f32_e32 v87, v103, v25
	v_mul_f32_e32 v104, 0x3d372713, v88
	v_mul_f32_e32 v105, 0x3d372713, v89
	v_mul_f32_e32 v106, 0x3d372713, v90
	v_mul_f32_e32 v107, 0x3d372713, v91
	v_mul_f32_e32 v108, 0x3d372713, v92
	v_mul_f32_e32 v109, 0x3d372713, v93
	v_mul_f32_e32 v110, 0x3d372713, v94
	v_mul_f32_e32 v111, 0x3d372713, v95
	v_mul_f32_e32 v104, v104, v88
	v_mul_f32_e32 v105, v105, v89
	v_mul_f32_e32 v106, v106, v90
	v_mul_f32_e32 v107, v107, v91
; __device__ __forceinline__ u32x4 pack8(const float (&f)[8]) { u32x4 o; o.x = cvt_pk_bf16(f[0], f[1]); o.y = cvt_pk_bf16(f[2], f[3]); o.z = cvt_pk_bf16(f[4], f[5]); o.w = cvt_pk_bf16(f[6], f[7]); return o; }
; __device__ __forceinline__ float gelu_tanh(float x) { return x * sigmoidf_(1.5957691216057308f * (x + 0.044715f * x * x * x)); }
; __device__ __forceinline__ void fixup_phase(KP p, int l) {
;     ...
;         for (int i = 0; i < 16; ++i) {
;             const size_t m = (size_t)(m0 + i);
;             float hl[8], pc[8], gr[8], o[8], h[8];
;             unpack8(__builtin_nontemporal_load((const u32x4*)(HLOC + m * D + c0)), hl); unpack8(__builtin_nontemporal_load((const u32x4*)(PCUM + m * D + c0)), pc);
;             bf16_t* gp = P + m * DP + C_GR + c0; unpack8(*(const u32x4*)gp, gr);
; #pragma unroll
;             for (int e = 0; e < 8; ++e) { h[e] = hl[e] + pc[e] * carry[e]; o[e] = gelu_tanh(gr[e]) * h[e]; }
;             *(u32x4*)gp = pack8(o);
	v_mul_f32_e32 v108, v108, v92
	v_mul_f32_e32 v109, v109, v93
	v_mul_f32_e32 v110, v110, v94
	v_mul_f32_e32 v111, v111, v95
	v_fma_f32 v104, v104, v88, v88
	v_fma_f32 v105, v105, v89, v89
	v_fma_f32 v106, v106, v90, v90
	v_fma_f32 v107, v107, v91, v91
	v_fma_f32 v108, v108, v92, v92
	v_fma_f32 v109, v109, v93, v93
	v_fma_f32 v110, v110, v94, v94
	v_fma_f32 v111, v111, v95, v95
	v_mul_f32_e32 v104, 0x3fcc422a, v104
	v_mul_f32_e32 v105, 0x3fcc422a, v105
	v_mul_f32_e32 v106, 0x3fcc422a, v106
	v_mul_f32_e32 v107, 0x3fcc422a, v107
	v_mul_f32_e32 v108, 0x3fcc422a, v108
	v_mul_f32_e32 v109, 0x3fcc422a, v109
	v_mul_f32_e32 v110, 0x3fcc422a, v110
	v_mul_f32_e32 v111, 0x3fcc422a, v111
	v_mul_f32_e32 v104, 0xbfb8aa3b, v104
	v_mul_f32_e32 v105, 0xbfb8aa3b, v105
	v_mul_f32_e32 v106, 0xbfb8aa3b, v106
	v_mul_f32_e32 v107, 0xbfb8aa3b, v107
	v_mul_f32_e32 v108, 0xbfb8aa3b, v108
	v_mul_f32_e32 v109, 0xbfb8aa3b, v109
	v_mul_f32_e32 v110, 0xbfb8aa3b, v110
	v_mul_f32_e32 v111, 0xbfb8aa3b, v111
	v_exp_f32_e32 v104, v104
	v_exp_f32_e32 v105, v105
	v_exp_f32_e32 v106, v106
	v_exp_f32_e32 v107, v107
	v_exp_f32_e32 v108, v108
	v_exp_f32_e32 v109, v109
	v_exp_f32_e32 v110, v110
	v_exp_f32_e32 v111, v111
	v_add_f32_e32 v104, 1.0, v104
	v_add_f32_e32 v105, 1.0, v105
	v_add_f32_e32 v106, 1.0, v106
	v_add_f32_e32 v107, 1.0, v107
	v_add_f32_e32 v108, 1.0, v108
	v_add_f32_e32 v109, 1.0, v109
	v_add_f32_e32 v110, 1.0, v110
	v_add_f32_e32 v111, 1.0, v111
	v_rcp_f32_e32 v104, v104
	v_rcp_f32_e32 v105, v105
	v_rcp_f32_e32 v106, v106
	v_rcp_f32_e32 v107, v107
	v_rcp_f32_e32 v108, v108
	v_rcp_f32_e32 v109, v109
	v_rcp_f32_e32 v110, v110
	v_rcp_f32_e32 v111, v111
	v_mul_f32_e32 v104, v104, v88
	v_mul_f32_e32 v105, v105, v89
	v_mul_f32_e32 v106, v106, v90
	v_mul_f32_e32 v107, v107, v91
	v_mul_f32_e32 v108, v108, v92
	v_mul_f32_e32 v109, v109, v93
	v_mul_f32_e32 v110, v110, v94
	v_mul_f32_e32 v111, v111, v95
	v_mul_f32_e32 v104, v80, v104
	v_mul_f32_e32 v105, v81, v105
	v_mul_f32_e32 v106, v82, v106
	v_mul_f32_e32 v107, v83, v107
	v_mul_f32_e32 v108, v84, v108
	v_mul_f32_e32 v109, v85, v109
	v_mul_f32_e32 v110, v86, v110
	v_mul_f32_e32 v111, v87, v111
	v_cvt_pk_bf16_f32 v112, v104, v105
	v_cvt_pk_bf16_f32 v113, v106, v107
	v_cvt_pk_bf16_f32 v114, v108, v109
	v_cvt_pk_bf16_f32 v115, v110, v111
	global_store_dwordx4 v27, v[112:115], s[24:25]
	s_add_u32 s24, s24, 0x2800
	s_addc_u32 s25, s25, 0
	global_load_dwordx4 v[68:71], v31, s[12:13]
	global_load_dwordx4 v[72:75], v31, s[12:13] offset:16
	global_load_dwordx4 v[76:79], v26, s[96:97] nt
	s_add_u32 s12, s12, 0x1000
	s_addc_u32 s13, s13, 0
	s_add_u32 s96, s96, 0x2800
	s_addc_u32 s97, s97, 0
	s_waitcnt vmcnt(12)
	v_lshlrev_b32_e32 v80, 16, v32
	v_and_b32_e32 v96, 0xffff0000, v32
	v_lshlrev_b32_e32 v81, 16, v33
	v_and_b32_e32 v97, 0xffff0000, v33
	v_lshlrev_b32_e32 v82, 16, v34
	v_and_b32_e32 v98, 0xffff0000, v34
	v_lshlrev_b32_e32 v83, 16, v35
	v_and_b32_e32 v99, 0xffff0000, v35
	v_lshlrev_b32_e32 v84, 16, v36
	v_and_b32_e32 v100, 0xffff0000, v36
	v_lshlrev_b32_e32 v85, 16, v37
	v_and_b32_e32 v101, 0xffff0000, v37
	v_lshlrev_b32_e32 v86, 16, v38
	v_and_b32_e32 v102, 0xffff0000, v38
	v_lshlrev_b32_e32 v87, 16, v39
	v_and_b32_e32 v103, 0xffff0000, v39
	v_lshlrev_b32_e32 v88, 16, v40
	v_and_b32_e32 v89, 0xffff0000, v40
	v_lshlrev_b32_e32 v90, 16, v41
	v_and_b32_e32 v91, 0xffff0000, v41
	v_lshlrev_b32_e32 v92, 16, v42
	v_and_b32_e32 v93, 0xffff0000, v42
	v_lshlrev_b32_e32 v94, 16, v43
	v_and_b32_e32 v95, 0xffff0000, v43
	v_fmac_f32_e32 v80, v96, v18
	v_fmac_f32_e32 v81, v97, v19
	v_fmac_f32_e32 v82, v98, v20
	v_fmac_f32_e32 v83, v99, v21
	v_fmac_f32_e32 v84, v100, v22
	v_fmac_f32_e32 v85, v101, v23
	v_fmac_f32_e32 v86, v102, v24
	v_fmac_f32_e32 v87, v103, v25
	v_mul_f32_e32 v104, 0x3d372713, v88
	v_mul_f32_e32 v105, 0x3d372713, v89
	v_mul_f32_e32 v106, 0x3d372713, v90
	v_mul_f32_e32 v107, 0x3d372713, v91
	v_mul_f32_e32 v108, 0x3d372713, v92
	v_mul_f32_e32 v109, 0x3d372713, v93
	v_mul_f32_e32 v110, 0x3d372713, v94
	v_mul_f32_e32 v111, 0x3d372713, v95
	v_mul_f32_e32 v104, v104, v88
	v_mul_f32_e32 v105, v105, v89
	v_mul_f32_e32 v106, v106, v90
	v_mul_f32_e32 v107, v107, v91
	v_mul_f32_e32 v108, v108, v92
	v_mul_f32_e32 v109, v109, v93
	v_mul_f32_e32 v110, v110, v94
	v_mul_f32_e32 v111, v111, v95
	v_fma_f32 v104, v104, v88, v88
	v_fma_f32 v105, v105, v89, v89
	v_fma_f32 v106, v106, v90, v90
	v_fma_f32 v107, v107, v91, v91
	v_fma_f32 v108, v108, v92, v92
	v_fma_f32 v109, v109, v93, v93
	v_fma_f32 v110, v110, v94, v94
	v_fma_f32 v111, v111, v95, v95
	v_mul_f32_e32 v104, 0x3fcc422a, v104
	v_mul_f32_e32 v105, 0x3fcc422a, v105
	v_mul_f32_e32 v106, 0x3fcc422a, v106
	v_mul_f32_e32 v107, 0x3fcc422a, v107
	v_mul_f32_e32 v108, 0x3fcc422a, v108
	v_mul_f32_e32 v109, 0x3fcc422a, v109
	v_mul_f32_e32 v110, 0x3fcc422a, v110
	v_mul_f32_e32 v111, 0x3fcc422a, v111
	v_mul_f32_e32 v104, 0xbfb8aa3b, v104
	v_mul_f32_e32 v105, 0xbfb8aa3b, v105
	v_mul_f32_e32 v106, 0xbfb8aa3b, v106
	v_mul_f32_e32 v107, 0xbfb8aa3b, v107
	v_mul_f32_e32 v108, 0xbfb8aa3b, v108
	v_mul_f32_e32 v109, 0xbfb8aa3b, v109
	v_mul_f32_e32 v110, 0xbfb8aa3b, v110
	v_mul_f32_e32 v111, 0xbfb8aa3b, v111
	v_exp_f32_e32 v104, v104
	v_exp_f32_e32 v105, v105
	v_exp_f32_e32 v106, v106
	v_exp_f32_e32 v107, v107
	v_exp_f32_e32 v108, v108
	v_exp_f32_e32 v109, v109
	v_exp_f32_e32 v110, v110
	v_exp_f32_e32 v111, v111
	v_add_f32_e32 v104, 1.0, v104
	v_add_f32_e32 v105, 1.0, v105
	v_add_f32_e32 v106, 1.0, v106
	v_add_f32_e32 v107, 1.0, v107
	v_add_f32_e32 v108, 1.0, v108
	v_add_f32_e32 v109, 1.0, v109
	v_add_f32_e32 v110, 1.0, v110
	v_add_f32_e32 v111, 1.0, v111
	v_rcp_f32_e32 v104, v104
	v_rcp_f32_e32 v105, v105
	v_rcp_f32_e32 v106, v106
	v_rcp_f32_e32 v107, v107
	v_rcp_f32_e32 v108, v108
	v_rcp_f32_e32 v109, v109
	v_rcp_f32_e32 v110, v110
	v_rcp_f32_e32 v111, v111
	v_mul_f32_e32 v104, v104, v88
	v_mul_f32_e32 v105, v105, v89
	v_mul_f32_e32 v106, v106, v90
	v_mul_f32_e32 v107, v107, v91
	v_mul_f32_e32 v108, v108, v92
	v_mul_f32_e32 v109, v109, v93
	v_mul_f32_e32 v110, v110, v94
	v_mul_f32_e32 v111, v111, v95
	v_mul_f32_e32 v104, v80, v104
	v_mul_f32_e32 v105, v81, v105
	v_mul_f32_e32 v106, v82, v106
	v_mul_f32_e32 v107, v83, v107
	v_mul_f32_e32 v108, v84, v108
	v_mul_f32_e32 v109, v85, v109
	v_mul_f32_e32 v110, v86, v110
	v_mul_f32_e32 v111, v87, v111
	v_cvt_pk_bf16_f32 v112, v104, v105
	v_cvt_pk_bf16_f32 v113, v106, v107
	v_cvt_pk_bf16_f32 v114, v108, v109
	v_cvt_pk_bf16_f32 v115, v110, v111
	global_store_dwordx4 v27, v[112:115], s[24:25]
	s_add_u32 s24, s24, 0x2800
	s_addc_u32 s25, s25, 0
	s_waitcnt vmcnt(9)
; __device__ __forceinline__ u32x4 pack8(const float (&f)[8]) { u32x4 o; o.x = cvt_pk_bf16(f[0], f[1]); o.y = cvt_pk_bf16(f[2], f[3]); o.z = cvt_pk_bf16(f[4], f[5]); o.w = cvt_pk_bf16(f[6], f[7]); return o; }
; __device__ __forceinline__ float gelu_tanh(float x) { return x * sigmoidf_(1.5957691216057308f * (x + 0.044715f * x * x * x)); }
; __device__ __forceinline__ void fixup_phase(KP p, int l) {
;     ...
;         for (int i = 0; i < 16; ++i) {
;             const size_t m = (size_t)(m0 + i);
;             float hl[8], pc[8], gr[8], o[8], h[8];
;             unpack8(__builtin_nontemporal_load((const u32x4*)(HLOC + m * D + c0)), hl); unpack8(__builtin_nontemporal_load((const u32x4*)(PCUM + m * D + c0)), pc);
;             bf16_t* gp = P + m * DP + C_GR + c0; unpack8(*(const u32x4*)gp, gr);
; #pragma unroll
;             for (int e = 0; e < 8; ++e) { h[e] = hl[e] + pc[e] * carry[e]; o[e] = gelu_tanh(gr[e]) * h[e]; }
;             *(u32x4*)gp = pack8(o);
	v_lshlrev_b32_e32 v80, 16, v44
	v_and_b32_e32 v96, 0xffff0000, v44
	v_lshlrev_b32_e32 v81, 16, v45
	v_and_b32_e32 v97, 0xffff0000, v45
	v_lshlrev_b32_e32 v82, 16, v46
	v_and_b32_e32 v98, 0xffff0000, v46
	v_lshlrev_b32_e32 v83, 16, v47
	v_and_b32_e32 v99, 0xffff0000, v47
	v_lshlrev_b32_e32 v84, 16, v48
	v_and_b32_e32 v100, 0xffff0000, v48
	v_lshlrev_b32_e32 v85, 16, v49
	v_and_b32_e32 v101, 0xffff0000, v49
	v_lshlrev_b32_e32 v86, 16, v50
	v_and_b32_e32 v102, 0xffff0000, v50
	v_lshlrev_b32_e32 v87, 16, v51
	v_and_b32_e32 v103, 0xffff0000, v51
	v_lshlrev_b32_e32 v88, 16, v52
	v_and_b32_e32 v89, 0xffff0000, v52
	v_lshlrev_b32_e32 v90, 16, v53
	v_and_b32_e32 v91, 0xffff0000, v53
	v_lshlrev_b32_e32 v92, 16, v54
	v_and_b32_e32 v93, 0xffff0000, v54
	v_lshlrev_b32_e32 v94, 16, v55
	v_and_b32_e32 v95, 0xffff0000, v55
	v_fmac_f32_e32 v80, v96, v18
	v_fmac_f32_e32 v81, v97, v19
	v_fmac_f32_e32 v82, v98, v20
	v_fmac_f32_e32 v83, v99, v21
	v_fmac_f32_e32 v84, v100, v22
	v_fmac_f32_e32 v85, v101, v23
	v_fmac_f32_e32 v86, v102, v24
	v_fmac_f32_e32 v87, v103, v25
	v_mul_f32_e32 v104, 0x3d372713, v88
	v_mul_f32_e32 v105, 0x3d372713, v89
	v_mul_f32_e32 v106, 0x3d372713, v90
	v_mul_f32_e32 v107, 0x3d372713, v91
	v_mul_f32_e32 v108, 0x3d372713, v92
	v_mul_f32_e32 v109, 0x3d372713, v93
	v_mul_f32_e32 v110, 0x3d372713, v94
	v_mul_f32_e32 v111, 0x3d372713, v95
	v_mul_f32_e32 v104, v104, v88
	v_mul_f32_e32 v105, v105, v89
	v_mul_f32_e32 v106, v106, v90
	v_mul_f32_e32 v107, v107, v91
	v_mul_f32_e32 v108, v108, v92
	v_mul_f32_e32 v109, v109, v93
	v_mul_f32_e32 v110, v110, v94
	v_mul_f32_e32 v111, v111, v95
	v_fma_f32 v104, v104, v88, v88
	v_fma_f32 v105, v105, v89, v89
	v_fma_f32 v106, v106, v90, v90
	v_fma_f32 v107, v107, v91, v91
	v_fma_f32 v108, v108, v92, v92
	v_fma_f32 v109, v109, v93, v93
	v_fma_f32 v110, v110, v94, v94
	v_fma_f32 v111, v111, v95, v95
	v_mul_f32_e32 v104, 0x3fcc422a, v104
	v_mul_f32_e32 v105, 0x3fcc422a, v105
	v_mul_f32_e32 v106, 0x3fcc422a, v106
	v_mul_f32_e32 v107, 0x3fcc422a, v107
	v_mul_f32_e32 v108, 0x3fcc422a, v108
	v_mul_f32_e32 v109, 0x3fcc422a, v109
	v_mul_f32_e32 v110, 0x3fcc422a, v110
	v_mul_f32_e32 v111, 0x3fcc422a, v111
	v_mul_f32_e32 v104, 0xbfb8aa3b, v104
	v_mul_f32_e32 v105, 0xbfb8aa3b, v105
	v_mul_f32_e32 v106, 0xbfb8aa3b, v106
	v_mul_f32_e32 v107, 0xbfb8aa3b, v107
	v_mul_f32_e32 v108, 0xbfb8aa3b, v108
	v_mul_f32_e32 v109, 0xbfb8aa3b, v109
	v_mul_f32_e32 v110, 0xbfb8aa3b, v110
	v_mul_f32_e32 v111, 0xbfb8aa3b, v111
	v_exp_f32_e32 v104, v104
	v_exp_f32_e32 v105, v105
	v_exp_f32_e32 v106, v106
	v_exp_f32_e32 v107, v107
	v_exp_f32_e32 v108, v108
	v_exp_f32_e32 v109, v109
	v_exp_f32_e32 v110, v110
	v_exp_f32_e32 v111, v111
	v_add_f32_e32 v104, 1.0, v104
	v_add_f32_e32 v105, 1.0, v105
	v_add_f32_e32 v106, 1.0, v106
	v_add_f32_e32 v107, 1.0, v107
	v_add_f32_e32 v108, 1.0, v108
	v_add_f32_e32 v109, 1.0, v109
	v_add_f32_e32 v110, 1.0, v110
	v_add_f32_e32 v111, 1.0, v111
	v_rcp_f32_e32 v104, v104
	v_rcp_f32_e32 v105, v105
	v_rcp_f32_e32 v106, v106
	v_rcp_f32_e32 v107, v107
	v_rcp_f32_e32 v108, v108
	v_rcp_f32_e32 v109, v109
	v_rcp_f32_e32 v110, v110
	v_rcp_f32_e32 v111, v111
	v_mul_f32_e32 v104, v104, v88
	v_mul_f32_e32 v105, v105, v89
	v_mul_f32_e32 v106, v106, v90
	v_mul_f32_e32 v107, v107, v91
	v_mul_f32_e32 v108, v108, v92
	v_mul_f32_e32 v109, v109, v93
	v_mul_f32_e32 v110, v110, v94
	v_mul_f32_e32 v111, v111, v95
	v_mul_f32_e32 v104, v80, v104
	v_mul_f32_e32 v105, v81, v105
	v_mul_f32_e32 v106, v82, v106
	v_mul_f32_e32 v107, v83, v107
	v_mul_f32_e32 v108, v84, v108
	v_mul_f32_e32 v109, v85, v109
	v_mul_f32_e32 v110, v86, v110
	v_mul_f32_e32 v111, v87, v111
	v_cvt_pk_bf16_f32 v112, v104, v105
	v_cvt_pk_bf16_f32 v113, v106, v107
	v_cvt_pk_bf16_f32 v114, v108, v109
	v_cvt_pk_bf16_f32 v115, v110, v111
	global_store_dwordx4 v27, v[112:115], s[24:25]
	s_add_u32 s24, s24, 0x2800
	s_addc_u32 s25, s25, 0
	s_waitcnt vmcnt(6)
	v_lshlrev_b32_e32 v80, 16, v56
	v_and_b32_e32 v96, 0xffff0000, v56
	v_lshlrev_b32_e32 v81, 16, v57
	v_and_b32_e32 v97, 0xffff0000, v57
	v_lshlrev_b32_e32 v82, 16, v58
	v_and_b32_e32 v98, 0xffff0000, v58
	v_lshlrev_b32_e32 v83, 16, v59
	v_and_b32_e32 v99, 0xffff0000, v59
	v_lshlrev_b32_e32 v84, 16, v60
	v_and_b32_e32 v100, 0xffff0000, v60
	v_lshlrev_b32_e32 v85, 16, v61
	v_and_b32_e32 v101, 0xffff0000, v61
	v_lshlrev_b32_e32 v86, 16, v62
	v_and_b32_e32 v102, 0xffff0000, v62
	v_lshlrev_b32_e32 v87, 16, v63
	v_and_b32_e32 v103, 0xffff0000, v63
	v_lshlrev_b32_e32 v88, 16, v64
	v_and_b32_e32 v89, 0xffff0000, v64
	v_lshlrev_b32_e32 v90, 16, v65
	v_and_b32_e32 v91, 0xffff0000, v65
	v_lshlrev_b32_e32 v92, 16, v66
	v_and_b32_e32 v93, 0xffff0000, v66
	v_lshlrev_b32_e32 v94, 16, v67
	v_and_b32_e32 v95, 0xffff0000, v67
	v_fmac_f32_e32 v80, v96, v18
	v_fmac_f32_e32 v81, v97, v19
	v_fmac_f32_e32 v82, v98, v20
	v_fmac_f32_e32 v83, v99, v21
	v_fmac_f32_e32 v84, v100, v22
	v_fmac_f32_e32 v85, v101, v23
	v_fmac_f32_e32 v86, v102, v24
	v_fmac_f32_e32 v87, v103, v25
	v_mul_f32_e32 v104, 0x3d372713, v88
	v_mul_f32_e32 v105, 0x3d372713, v89
	v_mul_f32_e32 v106, 0x3d372713, v90
	v_mul_f32_e32 v107, 0x3d372713, v91
	v_mul_f32_e32 v108, 0x3d372713, v92
	v_mul_f32_e32 v109, 0x3d372713, v93
	v_mul_f32_e32 v110, 0x3d372713, v94
	v_mul_f32_e32 v111, 0x3d372713, v95
	v_mul_f32_e32 v104, v104, v88
	v_mul_f32_e32 v105, v105, v89
	v_mul_f32_e32 v106, v106, v90
	v_mul_f32_e32 v107, v107, v91
	v_mul_f32_e32 v108, v108, v92
	v_mul_f32_e32 v109, v109, v93
	v_mul_f32_e32 v110, v110, v94
	v_mul_f32_e32 v111, v111, v95
	v_fma_f32 v104, v104, v88, v88
	v_fma_f32 v105, v105, v89, v89
	v_fma_f32 v106, v106, v90, v90
	v_fma_f32 v107, v107, v91, v91
; __device__ __forceinline__ u32x4 pack8(const float (&f)[8]) { u32x4 o; o.x = cvt_pk_bf16(f[0], f[1]); o.y = cvt_pk_bf16(f[2], f[3]); o.z = cvt_pk_bf16(f[4], f[5]); o.w = cvt_pk_bf16(f[6], f[7]); return o; }
; __device__ __forceinline__ float gelu_tanh(float x) { return x * sigmoidf_(1.5957691216057308f * (x + 0.044715f * x * x * x)); }
; __device__ __forceinline__ void fixup_phase(KP p, int l) {
;     ...
;         for (int i = 0; i < 16; ++i) {
;             const size_t m = (size_t)(m0 + i);
;             float hl[8], pc[8], gr[8], o[8], h[8];
;             unpack8(__builtin_nontemporal_load((const u32x4*)(HLOC + m * D + c0)), hl); unpack8(__builtin_nontemporal_load((const u32x4*)(PCUM + m * D + c0)), pc);
;             bf16_t* gp = P + m * DP + C_GR + c0; unpack8(*(const u32x4*)gp, gr);
; #pragma unroll
;             for (int e = 0; e < 8; ++e) { h[e] = hl[e] + pc[e] * carry[e]; o[e] = gelu_tanh(gr[e]) * h[e]; }
;             *(u32x4*)gp = pack8(o);
;             if (tile < 1032 && t0 + i == TP - 1) store8f(p->out + O_PRG + (size_t)(l * NB + b) * D + c0, h);
	v_fma_f32 v108, v108, v92, v92
	v_fma_f32 v109, v109, v93, v93
	v_fma_f32 v110, v110, v94, v94
	v_fma_f32 v111, v111, v95, v95
	v_mul_f32_e32 v104, 0x3fcc422a, v104
	v_mul_f32_e32 v105, 0x3fcc422a, v105
	v_mul_f32_e32 v106, 0x3fcc422a, v106
	v_mul_f32_e32 v107, 0x3fcc422a, v107
	v_mul_f32_e32 v108, 0x3fcc422a, v108
	v_mul_f32_e32 v109, 0x3fcc422a, v109
	v_mul_f32_e32 v110, 0x3fcc422a, v110
	v_mul_f32_e32 v111, 0x3fcc422a, v111
	v_mul_f32_e32 v104, 0xbfb8aa3b, v104
	v_mul_f32_e32 v105, 0xbfb8aa3b, v105
	v_mul_f32_e32 v106, 0xbfb8aa3b, v106
	v_mul_f32_e32 v107, 0xbfb8aa3b, v107
	v_mul_f32_e32 v108, 0xbfb8aa3b, v108
	v_mul_f32_e32 v109, 0xbfb8aa3b, v109
	v_mul_f32_e32 v110, 0xbfb8aa3b, v110
	v_mul_f32_e32 v111, 0xbfb8aa3b, v111
	v_exp_f32_e32 v104, v104
	v_exp_f32_e32 v105, v105
	v_exp_f32_e32 v106, v106
	v_exp_f32_e32 v107, v107
	v_exp_f32_e32 v108, v108
	v_exp_f32_e32 v109, v109
	v_exp_f32_e32 v110, v110
	v_exp_f32_e32 v111, v111
	v_add_f32_e32 v104, 1.0, v104
	v_add_f32_e32 v105, 1.0, v105
	v_add_f32_e32 v106, 1.0, v106
	v_add_f32_e32 v107, 1.0, v107
	v_add_f32_e32 v108, 1.0, v108
	v_add_f32_e32 v109, 1.0, v109
	v_add_f32_e32 v110, 1.0, v110
	v_add_f32_e32 v111, 1.0, v111
	v_rcp_f32_e32 v104, v104
	v_rcp_f32_e32 v105, v105
	v_rcp_f32_e32 v106, v106
	v_rcp_f32_e32 v107, v107
	v_rcp_f32_e32 v108, v108
	v_rcp_f32_e32 v109, v109
	v_rcp_f32_e32 v110, v110
	v_rcp_f32_e32 v111, v111
	v_mul_f32_e32 v104, v104, v88
	v_mul_f32_e32 v105, v105, v89
	v_mul_f32_e32 v106, v106, v90
	v_mul_f32_e32 v107, v107, v91
	v_mul_f32_e32 v108, v108, v92
	v_mul_f32_e32 v109, v109, v93
	v_mul_f32_e32 v110, v110, v94
	v_mul_f32_e32 v111, v111, v95
	v_mul_f32_e32 v104, v80, v104
	v_mul_f32_e32 v105, v81, v105
	v_mul_f32_e32 v106, v82, v106
	v_mul_f32_e32 v107, v83, v107
	v_mul_f32_e32 v108, v84, v108
	v_mul_f32_e32 v109, v85, v109
	v_mul_f32_e32 v110, v86, v110
	v_mul_f32_e32 v111, v87, v111
	v_cvt_pk_bf16_f32 v112, v104, v105
	v_cvt_pk_bf16_f32 v113, v106, v107
	v_cvt_pk_bf16_f32 v114, v108, v109
	v_cvt_pk_bf16_f32 v115, v110, v111
	global_store_dwordx4 v27, v[112:115], s[24:25]
	s_add_u32 s24, s24, 0x2800
	s_addc_u32 s25, s25, 0
	s_waitcnt vmcnt(3)
	v_lshlrev_b32_e32 v80, 16, v68
	v_and_b32_e32 v96, 0xffff0000, v68
	v_lshlrev_b32_e32 v81, 16, v69
	v_and_b32_e32 v97, 0xffff0000, v69
	v_lshlrev_b32_e32 v82, 16, v70
	v_and_b32_e32 v98, 0xffff0000, v70
	v_lshlrev_b32_e32 v83, 16, v71
	v_and_b32_e32 v99, 0xffff0000, v71
	v_lshlrev_b32_e32 v84, 16, v72
	v_and_b32_e32 v100, 0xffff0000, v72
	v_lshlrev_b32_e32 v85, 16, v73
	v_and_b32_e32 v101, 0xffff0000, v73
	v_lshlrev_b32_e32 v86, 16, v74
	v_and_b32_e32 v102, 0xffff0000, v74
	v_lshlrev_b32_e32 v87, 16, v75
	v_and_b32_e32 v103, 0xffff0000, v75
	v_lshlrev_b32_e32 v88, 16, v76
	v_and_b32_e32 v89, 0xffff0000, v76
	v_lshlrev_b32_e32 v90, 16, v77
	v_and_b32_e32 v91, 0xffff0000, v77
	v_lshlrev_b32_e32 v92, 16, v78
	v_and_b32_e32 v93, 0xffff0000, v78
	v_lshlrev_b32_e32 v94, 16, v79
	v_and_b32_e32 v95, 0xffff0000, v79
	v_fmac_f32_e32 v80, v96, v18
	v_fmac_f32_e32 v81, v97, v19
	v_fmac_f32_e32 v82, v98, v20
	v_fmac_f32_e32 v83, v99, v21
	v_fmac_f32_e32 v84, v100, v22
	v_fmac_f32_e32 v85, v101, v23
	v_fmac_f32_e32 v86, v102, v24
	v_fmac_f32_e32 v87, v103, v25
	v_mul_f32_e32 v104, 0x3d372713, v88
	v_mul_f32_e32 v105, 0x3d372713, v89
	v_mul_f32_e32 v106, 0x3d372713, v90
	v_mul_f32_e32 v107, 0x3d372713, v91
	v_mul_f32_e32 v108, 0x3d372713, v92
	v_mul_f32_e32 v109, 0x3d372713, v93
	v_mul_f32_e32 v110, 0x3d372713, v94
	v_mul_f32_e32 v111, 0x3d372713, v95
	v_mul_f32_e32 v104, v104, v88
	v_mul_f32_e32 v105, v105, v89
	v_mul_f32_e32 v106, v106, v90
	v_mul_f32_e32 v107, v107, v91
	v_mul_f32_e32 v108, v108, v92
	v_mul_f32_e32 v109, v109, v93
	v_mul_f32_e32 v110, v110, v94
	v_mul_f32_e32 v111, v111, v95
	v_fma_f32 v104, v104, v88, v88
	v_fma_f32 v105, v105, v89, v89
	v_fma_f32 v106, v106, v90, v90
	v_fma_f32 v107, v107, v91, v91
	v_fma_f32 v108, v108, v92, v92
	v_fma_f32 v109, v109, v93, v93
	v_fma_f32 v110, v110, v94, v94
	v_fma_f32 v111, v111, v95, v95
	v_mul_f32_e32 v104, 0x3fcc422a, v104
	v_mul_f32_e32 v105, 0x3fcc422a, v105
	v_mul_f32_e32 v106, 0x3fcc422a, v106
	v_mul_f32_e32 v107, 0x3fcc422a, v107
	v_mul_f32_e32 v108, 0x3fcc422a, v108
	v_mul_f32_e32 v109, 0x3fcc422a, v109
	v_mul_f32_e32 v110, 0x3fcc422a, v110
	v_mul_f32_e32 v111, 0x3fcc422a, v111
	v_mul_f32_e32 v104, 0xbfb8aa3b, v104
	v_mul_f32_e32 v105, 0xbfb8aa3b, v105
	v_mul_f32_e32 v106, 0xbfb8aa3b, v106
	v_mul_f32_e32 v107, 0xbfb8aa3b, v107
	v_mul_f32_e32 v108, 0xbfb8aa3b, v108
	v_mul_f32_e32 v109, 0xbfb8aa3b, v109
	v_mul_f32_e32 v110, 0xbfb8aa3b, v110
	v_mul_f32_e32 v111, 0xbfb8aa3b, v111
	v_exp_f32_e32 v104, v104
	v_exp_f32_e32 v105, v105
	v_exp_f32_e32 v106, v106
	v_exp_f32_e32 v107, v107
	v_exp_f32_e32 v108, v108
	v_exp_f32_e32 v109, v109
	v_exp_f32_e32 v110, v110
	v_exp_f32_e32 v111, v111
	v_add_f32_e32 v104, 1.0, v104
	v_add_f32_e32 v105, 1.0, v105
	v_add_f32_e32 v106, 1.0, v106
	v_add_f32_e32 v107, 1.0, v107
	v_add_f32_e32 v108, 1.0, v108
	v_add_f32_e32 v109, 1.0, v109
	v_add_f32_e32 v110, 1.0, v110
	v_add_f32_e32 v111, 1.0, v111
	v_rcp_f32_e32 v104, v104
	v_rcp_f32_e32 v105, v105
	v_rcp_f32_e32 v106, v106
	v_rcp_f32_e32 v107, v107
	v_rcp_f32_e32 v108, v108
	v_rcp_f32_e32 v109, v109
	v_rcp_f32_e32 v110, v110
	v_rcp_f32_e32 v111, v111
	v_mul_f32_e32 v104, v104, v88
	v_mul_f32_e32 v105, v105, v89
	v_mul_f32_e32 v106, v106, v90
	v_mul_f32_e32 v107, v107, v91
	v_mul_f32_e32 v108, v108, v92
	v_mul_f32_e32 v109, v109, v93
	v_mul_f32_e32 v110, v110, v94
	v_mul_f32_e32 v111, v111, v95
	v_mul_f32_e32 v104, v80, v104
	v_mul_f32_e32 v105, v81, v105
	v_mul_f32_e32 v106, v82, v106
	v_mul_f32_e32 v107, v83, v107
	v_mul_f32_e32 v108, v84, v108
	v_mul_f32_e32 v109, v85, v109
	v_mul_f32_e32 v110, v86, v110
	v_mul_f32_e32 v111, v87, v111
	v_cvt_pk_bf16_f32 v112, v104, v105
	v_cvt_pk_bf16_f32 v113, v106, v107
	v_cvt_pk_bf16_f32 v114, v108, v109
	v_cvt_pk_bf16_f32 v115, v110, v111
	global_store_dwordx4 v27, v[112:115], s[24:25]
	s_cmp_eq_u32 s43, 0
	s_cbranch_scc1 .Lfx_noprg
	s_lshl_b32 s44, s18, 12
	s_lshl_b32 s23, s10, 12
	s_add_i32 s44, s44, s23
	s_add_u32 s98, s72, 0x4120000
	s_addc_u32 s99, s73, 0
	s_add_u32 s98, s98, s44
	s_addc_u32 s99, s99, 0
	global_store_dwordx4 v31, v[80:83], s[98:99]
	global_store_dwordx4 v31, v[84:87], s[98:99] offset:16
